# GEMM MFMA order G9: accumulator pairs, q-major snake (12 srcA-shared transitions per segment instead of 12 srcB-shared)
# baseline (speedup 1.0000x reference)
.LBB0_200:
	ds_read_b128 v[148:151], v169
	ds_read_b128 v[152:155], v169 offset:1024
	ds_read_b128 v[156:159], v169 offset:2048
	ds_read_b128 v[160:163], v169 offset:3072
	ds_read_b128 v[174:177], v170
	ds_read_b128 v[178:181], v170 offset:1024
	ds_read_b128 v[182:185], v170 offset:2048
	ds_read_b128 v[186:189], v170 offset:3072
	s_add_u32 s26, s6, 0xfff00800
	s_addc_u32 s27, s7, -1
	s_cmp_eq_u32 s34, 60
	s_cselect_b32 s29, s17, s27
	s_cselect_b32 s28, s23, s26
	s_cselect_b32 s27, s15, s31
	s_cselect_b32 s26, s25, s30
	v_lshl_add_u64 v[190:191], s[6:7], 0, v[138:139]
	s_add_i32 m0, s41, 0xc000
	s_nop 0
	global_load_lds_dwordx4 v[190:191], off
	v_lshl_add_u64 v[190:191], s[6:7], 0, v[140:141]
	s_add_i32 m0, s41, 0xe000
	s_nop 0
	global_load_lds_dwordx4 v[190:191], off
	ds_read_b128 v[190:193], v171
	ds_read_b128 v[194:197], v171 offset:1024
	ds_read_b128 v[198:201], v171 offset:2048
	ds_read_b128 v[202:205], v171 offset:3072
	ds_read_b128 v[206:209], v171 offset:4096
	ds_read_b128 v[210:213], v171 offset:5120
	ds_read_b128 v[214:217], v171 offset:6144
	ds_read_b128 v[218:221], v171 offset:7168
	s_waitcnt vmcnt(8)
	s_waitcnt lgkmcnt(0)
	s_barrier
	s_waitcnt lgkmcnt(0)
	v_mfma_f32_16x16x32_bf16 v[124:127], v[148:151], v[190:193], v[124:127]
	v_mfma_f32_16x16x32_bf16 v[124:127], v[152:155], v[194:197], v[124:127]
	v_mfma_f32_16x16x32_bf16 v[116:119], v[152:155], v[202:205], v[116:119]
	v_mfma_f32_16x16x32_bf16 v[116:119], v[148:151], v[198:201], v[116:119]
	v_mfma_f32_16x16x32_bf16 v[108:111], v[148:151], v[206:209], v[108:111]
	v_mfma_f32_16x16x32_bf16 v[108:111], v[152:155], v[210:213], v[108:111]
	v_mfma_f32_16x16x32_bf16 v[100:103], v[152:155], v[218:221], v[100:103]
	v_mfma_f32_16x16x32_bf16 v[100:103], v[148:151], v[214:217], v[100:103]
	v_mfma_f32_16x16x32_bf16 v[96:99], v[156:159], v[214:217], v[96:99]
	v_mfma_f32_16x16x32_bf16 v[96:99], v[160:163], v[218:221], v[96:99]
	v_mfma_f32_16x16x32_bf16 v[104:107], v[160:163], v[210:213], v[104:107]
	v_mfma_f32_16x16x32_bf16 v[104:107], v[156:159], v[206:209], v[104:107]
	v_mfma_f32_16x16x32_bf16 v[112:115], v[156:159], v[198:201], v[112:115]
	v_mfma_f32_16x16x32_bf16 v[112:115], v[160:163], v[202:205], v[112:115]
	v_mfma_f32_16x16x32_bf16 v[120:123], v[160:163], v[194:197], v[120:123]
	v_mfma_f32_16x16x32_bf16 v[120:123], v[156:159], v[190:193], v[120:123]
	v_mfma_f32_16x16x32_bf16 v[60:63], v[174:177], v[190:193], v[60:63]
	v_mfma_f32_16x16x32_bf16 v[60:63], v[178:181], v[194:197], v[60:63]
	v_mfma_f32_16x16x32_bf16 v[52:55], v[178:181], v[202:205], v[52:55]
	v_mfma_f32_16x16x32_bf16 v[52:55], v[174:177], v[198:201], v[52:55]
	v_mfma_f32_16x16x32_bf16 v[44:47], v[174:177], v[206:209], v[44:47]
	v_mfma_f32_16x16x32_bf16 v[44:47], v[178:181], v[210:213], v[44:47]
	v_mfma_f32_16x16x32_bf16 v[36:39], v[178:181], v[218:221], v[36:39]
	v_mfma_f32_16x16x32_bf16 v[36:39], v[174:177], v[214:217], v[36:39]
	v_mfma_f32_16x16x32_bf16 v[32:35], v[182:185], v[214:217], v[32:35]
	v_mfma_f32_16x16x32_bf16 v[32:35], v[186:189], v[218:221], v[32:35]
	v_mfma_f32_16x16x32_bf16 v[40:43], v[186:189], v[210:213], v[40:43]
	v_mfma_f32_16x16x32_bf16 v[40:43], v[182:185], v[206:209], v[40:43]
	v_mfma_f32_16x16x32_bf16 v[48:51], v[182:185], v[198:201], v[48:51]
	v_mfma_f32_16x16x32_bf16 v[48:51], v[186:189], v[202:205], v[48:51]
	v_mfma_f32_16x16x32_bf16 v[56:59], v[186:189], v[194:197], v[56:59]
	v_mfma_f32_16x16x32_bf16 v[56:59], v[182:185], v[190:193], v[56:59]
	s_barrier
	s_add_i32 s35, s55, s36
	v_lshl_add_u64 v[222:223], s[26:27], 0, v[130:131]
	s_mov_b32 m0, s35
	v_lshl_add_u64 v[224:225], s[26:27], 0, v[134:135]
	global_load_lds_dwordx4 v[222:223], off
	s_add_i32 m0, s35, 0x2000
	s_add_u32 s58, s26, 0x100000
	s_addc_u32 s59, s27, 0
	s_add_i32 s35, s56, s36
	global_load_lds_dwordx4 v[224:225], off
	v_lshl_add_u64 v[190:191], s[58:59], 0, v[130:131]
	s_mov_b32 m0, s35
	v_lshl_add_u64 v[226:227], s[28:29], 0, v[128:129]
	global_load_lds_dwordx4 v[190:191], off
	v_lshl_add_u64 v[190:191], s[58:59], 0, v[134:135]
	s_add_i32 m0, s35, 0x2000
	v_lshl_add_u64 v[228:229], s[28:29], 0, v[132:133]
	global_load_lds_dwordx4 v[190:191], off
	s_mov_b32 m0, s41
	s_nop 0
	global_load_lds_dwordx4 v[226:227], off
	s_mov_b32 m0, s42
	s_nop 0
	global_load_lds_dwordx4 v[228:229], off
	ds_read_b128 v[190:193], v171 offset:16384
	ds_read_b128 v[194:197], v171 offset:17408
	ds_read_b128 v[198:201], v171 offset:18432
	ds_read_b128 v[202:205], v171 offset:19456
	ds_read_b128 v[206:209], v171 offset:20480
	ds_read_b128 v[210:213], v171 offset:21504
	ds_read_b128 v[214:217], v171 offset:22528
	ds_read_b128 v[218:221], v171 offset:23552
	s_waitcnt vmcnt(8)
	s_waitcnt lgkmcnt(0)
	s_barrier
	s_waitcnt lgkmcnt(0)
	v_mfma_f32_16x16x32_bf16 v[92:95], v[148:151], v[190:193], v[92:95]
	v_mfma_f32_16x16x32_bf16 v[92:95], v[152:155], v[194:197], v[92:95]
	v_mfma_f32_16x16x32_bf16 v[84:87], v[152:155], v[202:205], v[84:87]
	v_mfma_f32_16x16x32_bf16 v[84:87], v[148:151], v[198:201], v[84:87]
	v_mfma_f32_16x16x32_bf16 v[76:79], v[148:151], v[206:209], v[76:79]
	v_mfma_f32_16x16x32_bf16 v[76:79], v[152:155], v[210:213], v[76:79]
	v_mfma_f32_16x16x32_bf16 v[68:71], v[152:155], v[218:221], v[68:71]
	v_mfma_f32_16x16x32_bf16 v[68:71], v[148:151], v[214:217], v[68:71]
	v_mfma_f32_16x16x32_bf16 v[64:67], v[156:159], v[214:217], v[64:67]
	v_mfma_f32_16x16x32_bf16 v[64:67], v[160:163], v[218:221], v[64:67]
	v_mfma_f32_16x16x32_bf16 v[72:75], v[160:163], v[210:213], v[72:75]
	v_mfma_f32_16x16x32_bf16 v[72:75], v[156:159], v[206:209], v[72:75]
	v_mfma_f32_16x16x32_bf16 v[80:83], v[156:159], v[198:201], v[80:83]
	v_mfma_f32_16x16x32_bf16 v[80:83], v[160:163], v[202:205], v[80:83]
	v_mfma_f32_16x16x32_bf16 v[88:91], v[160:163], v[194:197], v[88:91]
	v_mfma_f32_16x16x32_bf16 v[88:91], v[156:159], v[190:193], v[88:91]
	v_mfma_f32_16x16x32_bf16 v[28:31], v[174:177], v[190:193], v[28:31]
	v_mfma_f32_16x16x32_bf16 v[28:31], v[178:181], v[194:197], v[28:31]
	v_mfma_f32_16x16x32_bf16 v[20:23], v[178:181], v[202:205], v[20:23]
	v_mfma_f32_16x16x32_bf16 v[20:23], v[174:177], v[198:201], v[20:23]
	v_mfma_f32_16x16x32_bf16 v[12:15], v[174:177], v[206:209], v[12:15]
	v_mfma_f32_16x16x32_bf16 v[12:15], v[178:181], v[210:213], v[12:15]
	v_mfma_f32_16x16x32_bf16 v[4:7], v[178:181], v[218:221], v[4:7]
	v_mfma_f32_16x16x32_bf16 v[4:7], v[174:177], v[214:217], v[4:7]
	v_mfma_f32_16x16x32_bf16 v[0:3], v[182:185], v[214:217], v[0:3]
	v_mfma_f32_16x16x32_bf16 v[0:3], v[186:189], v[218:221], v[0:3]
	v_mfma_f32_16x16x32_bf16 v[8:11], v[186:189], v[210:213], v[8:11]
	v_mfma_f32_16x16x32_bf16 v[8:11], v[182:185], v[206:209], v[8:11]
	v_mfma_f32_16x16x32_bf16 v[16:19], v[182:185], v[198:201], v[16:19]
	v_mfma_f32_16x16x32_bf16 v[16:19], v[186:189], v[202:205], v[16:19]
	v_mfma_f32_16x16x32_bf16 v[24:27], v[186:189], v[194:197], v[24:27]
	v_mfma_f32_16x16x32_bf16 v[24:27], v[182:185], v[190:193], v[24:27]
	s_barrier
	s_add_i32 s35, 0, 0x18000
	v_add_u32_e32 v136, s35, v165
	s_add_i32 s57, 0, 0x1c000
	ds_read_b128 v[148:151], v136
	ds_read_b128 v[152:155], v136 offset:1024
	ds_read_b128 v[156:159], v136 offset:2048
	ds_read_b128 v[160:163], v136 offset:3072
	v_add_u32_e32 v136, s57, v165
	ds_read_b128 v[174:177], v136
	ds_read_b128 v[178:181], v136 offset:1024
	ds_read_b128 v[182:185], v136 offset:2048
	ds_read_b128 v[186:189], v136 offset:3072
	s_add_u32 s28, s28, 0x100000
	s_addc_u32 s29, s29, 0
	s_mov_b32 m0, s43
	v_lshl_add_u64 v[190:191], s[28:29], 0, v[128:129]
	global_load_lds_dwordx4 v[190:191], off
	v_lshl_add_u64 v[190:191], s[28:29], 0, v[132:133]
	s_mov_b32 m0, s44
	s_nop 0
	global_load_lds_dwordx4 v[190:191], off
	ds_read_b128 v[190:193], v171 offset:32768
	ds_read_b128 v[194:197], v171 offset:33792
	ds_read_b128 v[198:201], v171 offset:34816
	ds_read_b128 v[202:205], v171 offset:35840
	ds_read_b128 v[206:209], v171 offset:36864
	ds_read_b128 v[210:213], v171 offset:37888
	ds_read_b128 v[214:217], v171 offset:38912
	ds_read_b128 v[218:221], v171 offset:39936
	s_waitcnt vmcnt(8)
	s_waitcnt lgkmcnt(0)
	s_barrier
	s_waitcnt lgkmcnt(0)
	v_mfma_f32_16x16x32_bf16 v[124:127], v[148:151], v[190:193], v[124:127]
	v_mfma_f32_16x16x32_bf16 v[124:127], v[152:155], v[194:197], v[124:127]
	v_mfma_f32_16x16x32_bf16 v[116:119], v[152:155], v[202:205], v[116:119]
	v_mfma_f32_16x16x32_bf16 v[116:119], v[148:151], v[198:201], v[116:119]
	v_mfma_f32_16x16x32_bf16 v[108:111], v[148:151], v[206:209], v[108:111]
	v_mfma_f32_16x16x32_bf16 v[108:111], v[152:155], v[210:213], v[108:111]
	v_mfma_f32_16x16x32_bf16 v[100:103], v[152:155], v[218:221], v[100:103]
	v_mfma_f32_16x16x32_bf16 v[100:103], v[148:151], v[214:217], v[100:103]
	v_mfma_f32_16x16x32_bf16 v[96:99], v[156:159], v[214:217], v[96:99]
	v_mfma_f32_16x16x32_bf16 v[96:99], v[160:163], v[218:221], v[96:99]
	v_mfma_f32_16x16x32_bf16 v[104:107], v[160:163], v[210:213], v[104:107]
	v_mfma_f32_16x16x32_bf16 v[104:107], v[156:159], v[206:209], v[104:107]
	v_mfma_f32_16x16x32_bf16 v[112:115], v[156:159], v[198:201], v[112:115]
	v_mfma_f32_16x16x32_bf16 v[112:115], v[160:163], v[202:205], v[112:115]
	v_mfma_f32_16x16x32_bf16 v[120:123], v[160:163], v[194:197], v[120:123]
	v_mfma_f32_16x16x32_bf16 v[120:123], v[156:159], v[190:193], v[120:123]
	v_mfma_f32_16x16x32_bf16 v[60:63], v[174:177], v[190:193], v[60:63]
	v_mfma_f32_16x16x32_bf16 v[60:63], v[178:181], v[194:197], v[60:63]
	v_mfma_f32_16x16x32_bf16 v[52:55], v[178:181], v[202:205], v[52:55]
	v_mfma_f32_16x16x32_bf16 v[52:55], v[174:177], v[198:201], v[52:55]
	v_mfma_f32_16x16x32_bf16 v[44:47], v[174:177], v[206:209], v[44:47]
	v_mfma_f32_16x16x32_bf16 v[44:47], v[178:181], v[210:213], v[44:47]
	v_mfma_f32_16x16x32_bf16 v[36:39], v[178:181], v[218:221], v[36:39]
	v_mfma_f32_16x16x32_bf16 v[36:39], v[174:177], v[214:217], v[36:39]
	v_mfma_f32_16x16x32_bf16 v[32:35], v[182:185], v[214:217], v[32:35]
	v_mfma_f32_16x16x32_bf16 v[32:35], v[186:189], v[218:221], v[32:35]
	v_mfma_f32_16x16x32_bf16 v[40:43], v[186:189], v[210:213], v[40:43]
	v_mfma_f32_16x16x32_bf16 v[40:43], v[182:185], v[206:209], v[40:43]
	v_mfma_f32_16x16x32_bf16 v[48:51], v[182:185], v[198:201], v[48:51]
	v_mfma_f32_16x16x32_bf16 v[48:51], v[186:189], v[202:205], v[48:51]
	v_mfma_f32_16x16x32_bf16 v[56:59], v[186:189], v[194:197], v[56:59]
	v_mfma_f32_16x16x32_bf16 v[56:59], v[182:185], v[190:193], v[56:59]
	s_barrier
	s_add_i32 s28, s35, s36
	v_lshl_add_u64 v[190:191], v[222:223], 0, s[12:13]
	s_mov_b32 m0, s28
	s_nop 0
	global_load_lds_dwordx4 v[190:191], off
	s_add_i32 m0, s28, 0x2000
	s_add_u32 s26, s26, 0x100800
	v_lshl_add_u64 v[190:191], v[224:225], 0, s[12:13]
	s_addc_u32 s27, s27, 0
	s_add_i32 s28, s57, s36
	global_load_lds_dwordx4 v[190:191], off
	v_lshl_add_u64 v[190:191], s[26:27], 0, v[130:131]
	s_mov_b32 m0, s28
	s_nop 0
	global_load_lds_dwordx4 v[190:191], off
	v_lshl_add_u64 v[190:191], s[26:27], 0, v[134:135]
	s_add_i32 m0, s28, 0x2000
	s_nop 0
	global_load_lds_dwordx4 v[190:191], off
	v_lshl_add_u64 v[190:191], v[226:227], 0, s[12:13]
	s_mov_b32 m0, s49
	s_nop 0
	global_load_lds_dwordx4 v[190:191], off
	v_lshl_add_u64 v[190:191], v[228:229], 0, s[12:13]
	s_mov_b32 m0, s50
	s_nop 0
	global_load_lds_dwordx4 v[190:191], off
	ds_read_b128 v[190:193], v171 offset:49152
	ds_read_b128 v[194:197], v171 offset:50176
	ds_read_b128 v[198:201], v171 offset:51200
	ds_read_b128 v[202:205], v171 offset:52224
	ds_read_b128 v[206:209], v171 offset:53248
	ds_read_b128 v[210:213], v171 offset:54272
	ds_read_b128 v[214:217], v171 offset:55296
	ds_read_b128 v[218:221], v171 offset:56320
	s_waitcnt vmcnt(8)
	s_waitcnt lgkmcnt(0)
	s_barrier
	s_waitcnt lgkmcnt(0)
	v_mfma_f32_16x16x32_bf16 v[92:95], v[148:151], v[190:193], v[92:95]
	v_mfma_f32_16x16x32_bf16 v[92:95], v[152:155], v[194:197], v[92:95]
	v_mfma_f32_16x16x32_bf16 v[84:87], v[152:155], v[202:205], v[84:87]
	v_mfma_f32_16x16x32_bf16 v[84:87], v[148:151], v[198:201], v[84:87]
	v_mfma_f32_16x16x32_bf16 v[76:79], v[148:151], v[206:209], v[76:79]
	v_mfma_f32_16x16x32_bf16 v[76:79], v[152:155], v[210:213], v[76:79]
	v_mfma_f32_16x16x32_bf16 v[68:71], v[152:155], v[218:221], v[68:71]
	v_mfma_f32_16x16x32_bf16 v[68:71], v[148:151], v[214:217], v[68:71]
	v_mfma_f32_16x16x32_bf16 v[64:67], v[156:159], v[214:217], v[64:67]
	v_mfma_f32_16x16x32_bf16 v[64:67], v[160:163], v[218:221], v[64:67]
	v_mfma_f32_16x16x32_bf16 v[72:75], v[160:163], v[210:213], v[72:75]
	v_mfma_f32_16x16x32_bf16 v[72:75], v[156:159], v[206:209], v[72:75]
	v_mfma_f32_16x16x32_bf16 v[80:83], v[156:159], v[198:201], v[80:83]
	v_mfma_f32_16x16x32_bf16 v[80:83], v[160:163], v[202:205], v[80:83]
	v_mfma_f32_16x16x32_bf16 v[88:91], v[160:163], v[194:197], v[88:91]
	v_mfma_f32_16x16x32_bf16 v[88:91], v[156:159], v[190:193], v[88:91]
	v_mfma_f32_16x16x32_bf16 v[28:31], v[174:177], v[190:193], v[28:31]
	v_mfma_f32_16x16x32_bf16 v[28:31], v[178:181], v[194:197], v[28:31]
	v_mfma_f32_16x16x32_bf16 v[20:23], v[178:181], v[202:205], v[20:23]
	v_mfma_f32_16x16x32_bf16 v[20:23], v[174:177], v[198:201], v[20:23]
	v_mfma_f32_16x16x32_bf16 v[12:15], v[174:177], v[206:209], v[12:15]
	v_mfma_f32_16x16x32_bf16 v[12:15], v[178:181], v[210:213], v[12:15]
	v_mfma_f32_16x16x32_bf16 v[4:7], v[178:181], v[218:221], v[4:7]
	v_mfma_f32_16x16x32_bf16 v[4:7], v[174:177], v[214:217], v[4:7]
	v_mfma_f32_16x16x32_bf16 v[0:3], v[182:185], v[214:217], v[0:3]
	v_mfma_f32_16x16x32_bf16 v[0:3], v[186:189], v[218:221], v[0:3]
	v_mfma_f32_16x16x32_bf16 v[8:11], v[186:189], v[210:213], v[8:11]
	v_mfma_f32_16x16x32_bf16 v[8:11], v[182:185], v[206:209], v[8:11]
	v_mfma_f32_16x16x32_bf16 v[16:19], v[182:185], v[198:201], v[16:19]
	v_mfma_f32_16x16x32_bf16 v[16:19], v[186:189], v[202:205], v[16:19]
	v_mfma_f32_16x16x32_bf16 v[24:27], v[186:189], v[194:197], v[24:27]
	v_mfma_f32_16x16x32_bf16 v[24:27], v[182:185], v[190:193], v[24:27]
	s_barrier
	s_add_i32 s34, s34, 2
	s_add_u32 s6, s6, 0x1000
	s_addc_u32 s7, s7, 0
	s_add_u32 s30, s30, 0x1000
	s_addc_u32 s31, s31, 0
	s_cmp_gt_u32 s34, 61
	s_cbranch_scc0 .LBB0_200
	s_and_b64 vcc, exec, s[0:1]
	s_cbranch_vccz .LBB0_203
	s_barrier

.LBB0_333:
	ds_read_b128 v[144:147], v152
	ds_read_b128 v[156:159], v152 offset:1024
	ds_read_b128 v[160:163], v152 offset:2048
	ds_read_b128 v[164:167], v152 offset:3072
	ds_read_b128 v[168:171], v153
	ds_read_b128 v[172:175], v153 offset:1024
	ds_read_b128 v[176:179], v153 offset:2048
	ds_read_b128 v[180:183], v153 offset:3072
	s_add_u32 s28, s24, 0x100
	s_addc_u32 s29, s25, 0
	s_cmp_eq_u32 s56, 60
	s_cselect_b32 s35, s13, s29
	s_cselect_b32 s34, s52, s28
	s_cselect_b32 s31, s11, s55
	s_cselect_b32 s30, s53, s54
	v_lshl_add_u64 v[184:185], s[24:25], 0, v[136:137]
	s_add_i32 m0, s21, 0xc000
	s_nop 0
	global_load_lds_dwordx4 v[184:185], off
	v_lshl_add_u64 v[184:185], s[24:25], 0, v[138:139]
	s_add_i32 m0, s21, 0xe000
	s_nop 0
	global_load_lds_dwordx4 v[184:185], off
	ds_read_b128 v[184:187], v154
	ds_read_b128 v[188:191], v154 offset:1024
	ds_read_b128 v[192:195], v154 offset:2048
	ds_read_b128 v[196:199], v154 offset:3072
	ds_read_b128 v[200:203], v154 offset:4096
	ds_read_b128 v[204:207], v154 offset:5120
	ds_read_b128 v[208:211], v154 offset:6144
	ds_read_b128 v[212:215], v154 offset:7168
	s_waitcnt vmcnt(8)
	s_waitcnt lgkmcnt(0)
	s_barrier
	s_waitcnt lgkmcnt(0)
	v_mfma_f32_16x16x32_bf16 v[124:127], v[144:147], v[184:187], v[124:127]
	v_mfma_f32_16x16x32_bf16 v[124:127], v[156:159], v[188:191], v[124:127]
	v_mfma_f32_16x16x32_bf16 v[116:119], v[156:159], v[196:199], v[116:119]
	v_mfma_f32_16x16x32_bf16 v[116:119], v[144:147], v[192:195], v[116:119]
	v_mfma_f32_16x16x32_bf16 v[100:103], v[144:147], v[200:203], v[100:103]
	v_mfma_f32_16x16x32_bf16 v[100:103], v[156:159], v[204:207], v[100:103]
	v_mfma_f32_16x16x32_bf16 v[84:87], v[156:159], v[212:215], v[84:87]
	v_mfma_f32_16x16x32_bf16 v[84:87], v[144:147], v[208:211], v[84:87]
	v_mfma_f32_16x16x32_bf16 v[76:79], v[160:163], v[208:211], v[76:79]
	v_mfma_f32_16x16x32_bf16 v[76:79], v[164:167], v[212:215], v[76:79]
	v_mfma_f32_16x16x32_bf16 v[92:95], v[164:167], v[204:207], v[92:95]
	v_mfma_f32_16x16x32_bf16 v[92:95], v[160:163], v[200:203], v[92:95]
	v_mfma_f32_16x16x32_bf16 v[108:111], v[160:163], v[192:195], v[108:111]
	v_mfma_f32_16x16x32_bf16 v[108:111], v[164:167], v[196:199], v[108:111]
	v_mfma_f32_16x16x32_bf16 v[120:123], v[164:167], v[188:191], v[120:123]
	v_mfma_f32_16x16x32_bf16 v[120:123], v[160:163], v[184:187], v[120:123]
	v_mfma_f32_16x16x32_bf16 v[112:115], v[168:171], v[184:187], v[112:115]
	v_mfma_f32_16x16x32_bf16 v[112:115], v[172:175], v[188:191], v[112:115]
	v_mfma_f32_16x16x32_bf16 v[96:99], v[172:175], v[196:199], v[96:99]
	v_mfma_f32_16x16x32_bf16 v[96:99], v[168:171], v[192:195], v[96:99]
	v_mfma_f32_16x16x32_bf16 v[80:83], v[168:171], v[200:203], v[80:83]
	v_mfma_f32_16x16x32_bf16 v[80:83], v[172:175], v[204:207], v[80:83]
	v_mfma_f32_16x16x32_bf16 v[68:71], v[172:175], v[212:215], v[68:71]
	v_mfma_f32_16x16x32_bf16 v[68:71], v[168:171], v[208:211], v[68:71]
	v_mfma_f32_16x16x32_bf16 v[64:67], v[176:179], v[208:211], v[64:67]
	v_mfma_f32_16x16x32_bf16 v[64:67], v[180:183], v[212:215], v[64:67]
	v_mfma_f32_16x16x32_bf16 v[72:75], v[180:183], v[204:207], v[72:75]
	v_mfma_f32_16x16x32_bf16 v[72:75], v[176:179], v[200:203], v[72:75]
	v_mfma_f32_16x16x32_bf16 v[88:91], v[176:179], v[192:195], v[88:91]
	v_mfma_f32_16x16x32_bf16 v[88:91], v[180:183], v[196:199], v[88:91]
	v_mfma_f32_16x16x32_bf16 v[104:107], v[180:183], v[188:191], v[104:107]
	v_mfma_f32_16x16x32_bf16 v[104:107], v[176:179], v[184:187], v[104:107]
	s_barrier
	s_add_i32 s24, s49, s41
	v_lshl_add_u64 v[216:217], s[30:31], 0, v[130:131]
	s_mov_b32 m0, s24
	v_lshl_add_u64 v[218:219], s[30:31], 0, v[134:135]
	global_load_lds_dwordx4 v[216:217], off
	s_add_i32 m0, s24, 0x2000
	s_add_u32 s24, s30, 0x100000
	s_addc_u32 s25, s31, 0
	s_add_i32 s57, s50, s41
	global_load_lds_dwordx4 v[218:219], off
	v_lshl_add_u64 v[184:185], s[24:25], 0, v[130:131]
	s_mov_b32 m0, s57
	v_lshl_add_u64 v[220:221], s[34:35], 0, v[128:129]
	global_load_lds_dwordx4 v[184:185], off
	v_lshl_add_u64 v[184:185], s[24:25], 0, v[134:135]
	s_add_i32 m0, s57, 0x2000
	v_lshl_add_u64 v[222:223], s[34:35], 0, v[132:133]
	global_load_lds_dwordx4 v[184:185], off
	s_mov_b32 m0, s21
	s_nop 0
	global_load_lds_dwordx4 v[220:221], off
	s_mov_b32 m0, s42
	s_nop 0
	global_load_lds_dwordx4 v[222:223], off
	ds_read_b128 v[184:187], v154 offset:16384
	ds_read_b128 v[188:191], v154 offset:17408
	ds_read_b128 v[192:195], v154 offset:18432
	ds_read_b128 v[196:199], v154 offset:19456
	ds_read_b128 v[200:203], v154 offset:20480
	ds_read_b128 v[204:207], v154 offset:21504
	ds_read_b128 v[208:211], v154 offset:22528
	ds_read_b128 v[212:215], v154 offset:23552
	s_waitcnt vmcnt(8)
	s_waitcnt lgkmcnt(0)
	s_barrier
	s_waitcnt lgkmcnt(0)
	v_mfma_f32_16x16x32_bf16 v[60:63], v[144:147], v[184:187], v[60:63]
	v_mfma_f32_16x16x32_bf16 v[60:63], v[156:159], v[188:191], v[60:63]
	v_mfma_f32_16x16x32_bf16 v[52:55], v[156:159], v[196:199], v[52:55]
	v_mfma_f32_16x16x32_bf16 v[52:55], v[144:147], v[192:195], v[52:55]
	v_mfma_f32_16x16x32_bf16 v[36:39], v[144:147], v[200:203], v[36:39]
	v_mfma_f32_16x16x32_bf16 v[36:39], v[156:159], v[204:207], v[36:39]
	v_mfma_f32_16x16x32_bf16 v[20:23], v[156:159], v[212:215], v[20:23]
	v_mfma_f32_16x16x32_bf16 v[20:23], v[144:147], v[208:211], v[20:23]
	v_mfma_f32_16x16x32_bf16 v[12:15], v[160:163], v[208:211], v[12:15]
	v_mfma_f32_16x16x32_bf16 v[12:15], v[164:167], v[212:215], v[12:15]
	v_mfma_f32_16x16x32_bf16 v[28:31], v[164:167], v[204:207], v[28:31]
	v_mfma_f32_16x16x32_bf16 v[28:31], v[160:163], v[200:203], v[28:31]
	v_mfma_f32_16x16x32_bf16 v[44:47], v[160:163], v[192:195], v[44:47]
	v_mfma_f32_16x16x32_bf16 v[44:47], v[164:167], v[196:199], v[44:47]
	v_mfma_f32_16x16x32_bf16 v[56:59], v[164:167], v[188:191], v[56:59]
	v_mfma_f32_16x16x32_bf16 v[56:59], v[160:163], v[184:187], v[56:59]
	v_mfma_f32_16x16x32_bf16 v[48:51], v[168:171], v[184:187], v[48:51]
	v_mfma_f32_16x16x32_bf16 v[48:51], v[172:175], v[188:191], v[48:51]
	v_mfma_f32_16x16x32_bf16 v[32:35], v[172:175], v[196:199], v[32:35]
	v_mfma_f32_16x16x32_bf16 v[32:35], v[168:171], v[192:195], v[32:35]
	v_mfma_f32_16x16x32_bf16 v[16:19], v[168:171], v[200:203], v[16:19]
	v_mfma_f32_16x16x32_bf16 v[16:19], v[172:175], v[204:207], v[16:19]
	v_mfma_f32_16x16x32_bf16 v[4:7], v[172:175], v[212:215], v[4:7]
	v_mfma_f32_16x16x32_bf16 v[4:7], v[168:171], v[208:211], v[4:7]
	v_mfma_f32_16x16x32_bf16 v[0:3], v[176:179], v[208:211], v[0:3]
	v_mfma_f32_16x16x32_bf16 v[0:3], v[180:183], v[212:215], v[0:3]
	v_mfma_f32_16x16x32_bf16 v[8:11], v[180:183], v[204:207], v[8:11]
	v_mfma_f32_16x16x32_bf16 v[8:11], v[176:179], v[200:203], v[8:11]
	v_mfma_f32_16x16x32_bf16 v[24:27], v[176:179], v[192:195], v[24:27]
	v_mfma_f32_16x16x32_bf16 v[24:27], v[180:183], v[196:199], v[24:27]
	v_mfma_f32_16x16x32_bf16 v[40:43], v[180:183], v[188:191], v[40:43]
	v_mfma_f32_16x16x32_bf16 v[40:43], v[176:179], v[184:187], v[40:43]
	s_barrier
	s_add_i32 s57, 0, 0x18000
	v_add_u32_e32 v155, s57, v149
	s_add_i32 s58, 0, 0x1c000
	ds_read_b128 v[144:147], v155
	ds_read_b128 v[156:159], v155 offset:1024
	ds_read_b128 v[160:163], v155 offset:2048
	ds_read_b128 v[164:167], v155 offset:3072
	v_add_u32_e32 v155, s58, v149
	ds_read_b128 v[168:171], v155
	ds_read_b128 v[172:175], v155 offset:1024
	ds_read_b128 v[176:179], v155 offset:2048
	ds_read_b128 v[180:183], v155 offset:3072
	s_add_u32 s24, s34, 0x100000
	s_addc_u32 s25, s35, 0
	s_mov_b32 m0, s43
	v_lshl_add_u64 v[184:185], s[24:25], 0, v[128:129]
	global_load_lds_dwordx4 v[184:185], off
	v_lshl_add_u64 v[184:185], s[24:25], 0, v[132:133]
	s_mov_b32 m0, s44
	s_nop 0
	global_load_lds_dwordx4 v[184:185], off
	ds_read_b128 v[184:187], v154 offset:32768
	ds_read_b128 v[188:191], v154 offset:33792
	ds_read_b128 v[192:195], v154 offset:34816
	ds_read_b128 v[196:199], v154 offset:35840
	ds_read_b128 v[200:203], v154 offset:36864
	ds_read_b128 v[204:207], v154 offset:37888
	ds_read_b128 v[208:211], v154 offset:38912
	ds_read_b128 v[212:215], v154 offset:39936
	s_waitcnt vmcnt(8)
	s_waitcnt lgkmcnt(0)
	s_barrier
	s_waitcnt lgkmcnt(0)
	v_mfma_f32_16x16x32_bf16 v[124:127], v[144:147], v[184:187], v[124:127]
	v_mfma_f32_16x16x32_bf16 v[124:127], v[156:159], v[188:191], v[124:127]
	v_mfma_f32_16x16x32_bf16 v[116:119], v[156:159], v[196:199], v[116:119]
	v_mfma_f32_16x16x32_bf16 v[116:119], v[144:147], v[192:195], v[116:119]
	v_mfma_f32_16x16x32_bf16 v[100:103], v[144:147], v[200:203], v[100:103]
	v_mfma_f32_16x16x32_bf16 v[100:103], v[156:159], v[204:207], v[100:103]
	v_mfma_f32_16x16x32_bf16 v[84:87], v[156:159], v[212:215], v[84:87]
	v_mfma_f32_16x16x32_bf16 v[84:87], v[144:147], v[208:211], v[84:87]
	v_mfma_f32_16x16x32_bf16 v[76:79], v[160:163], v[208:211], v[76:79]
	v_mfma_f32_16x16x32_bf16 v[76:79], v[164:167], v[212:215], v[76:79]
	v_mfma_f32_16x16x32_bf16 v[92:95], v[164:167], v[204:207], v[92:95]
	v_mfma_f32_16x16x32_bf16 v[92:95], v[160:163], v[200:203], v[92:95]
	v_mfma_f32_16x16x32_bf16 v[108:111], v[160:163], v[192:195], v[108:111]
	v_mfma_f32_16x16x32_bf16 v[108:111], v[164:167], v[196:199], v[108:111]
	v_mfma_f32_16x16x32_bf16 v[120:123], v[164:167], v[188:191], v[120:123]
	v_mfma_f32_16x16x32_bf16 v[120:123], v[160:163], v[184:187], v[120:123]
	v_mfma_f32_16x16x32_bf16 v[112:115], v[168:171], v[184:187], v[112:115]
	v_mfma_f32_16x16x32_bf16 v[112:115], v[172:175], v[188:191], v[112:115]
	v_mfma_f32_16x16x32_bf16 v[96:99], v[172:175], v[196:199], v[96:99]
	v_mfma_f32_16x16x32_bf16 v[96:99], v[168:171], v[192:195], v[96:99]
	v_mfma_f32_16x16x32_bf16 v[80:83], v[168:171], v[200:203], v[80:83]
	v_mfma_f32_16x16x32_bf16 v[80:83], v[172:175], v[204:207], v[80:83]
	v_mfma_f32_16x16x32_bf16 v[68:71], v[172:175], v[212:215], v[68:71]
	v_mfma_f32_16x16x32_bf16 v[68:71], v[168:171], v[208:211], v[68:71]
	v_mfma_f32_16x16x32_bf16 v[64:67], v[176:179], v[208:211], v[64:67]
	v_mfma_f32_16x16x32_bf16 v[64:67], v[180:183], v[212:215], v[64:67]
	v_mfma_f32_16x16x32_bf16 v[72:75], v[180:183], v[204:207], v[72:75]
	v_mfma_f32_16x16x32_bf16 v[72:75], v[176:179], v[200:203], v[72:75]
	v_mfma_f32_16x16x32_bf16 v[88:91], v[176:179], v[192:195], v[88:91]
	v_mfma_f32_16x16x32_bf16 v[88:91], v[180:183], v[196:199], v[88:91]
	v_mfma_f32_16x16x32_bf16 v[104:107], v[180:183], v[188:191], v[104:107]
	v_mfma_f32_16x16x32_bf16 v[104:107], v[176:179], v[184:187], v[104:107]
	s_barrier
	s_add_i32 s24, s57, s41
	v_lshl_add_u64 v[184:185], v[216:217], 0, s[8:9]
	s_mov_b32 m0, s24
	s_nop 0
	global_load_lds_dwordx4 v[184:185], off
	s_add_i32 m0, s24, 0x2000
	s_add_u32 s24, s30, 0x100080
	v_lshl_add_u64 v[184:185], v[218:219], 0, s[8:9]
	s_addc_u32 s25, s31, 0
	s_add_i32 s30, s58, s41
	global_load_lds_dwordx4 v[184:185], off
	v_lshl_add_u64 v[184:185], s[24:25], 0, v[130:131]
	s_mov_b32 m0, s30
	s_nop 0
	global_load_lds_dwordx4 v[184:185], off
	v_lshl_add_u64 v[184:185], s[24:25], 0, v[134:135]
	s_add_i32 m0, s30, 0x2000
	s_nop 0
	global_load_lds_dwordx4 v[184:185], off
	v_lshl_add_u64 v[184:185], v[220:221], 0, s[8:9]
	s_mov_b32 m0, s46
	s_nop 0
	global_load_lds_dwordx4 v[184:185], off
	v_lshl_add_u64 v[184:185], v[222:223], 0, s[8:9]
	s_mov_b32 m0, s47
	s_nop 0
	global_load_lds_dwordx4 v[184:185], off
	ds_read_b128 v[184:187], v154 offset:49152
	ds_read_b128 v[188:191], v154 offset:50176
	ds_read_b128 v[192:195], v154 offset:51200
	ds_read_b128 v[196:199], v154 offset:52224
	ds_read_b128 v[200:203], v154 offset:53248
	ds_read_b128 v[204:207], v154 offset:54272
	ds_read_b128 v[208:211], v154 offset:55296
	ds_read_b128 v[212:215], v154 offset:56320
	s_waitcnt vmcnt(8)
	s_waitcnt lgkmcnt(0)
	s_barrier
	s_waitcnt lgkmcnt(0)
	v_mfma_f32_16x16x32_bf16 v[60:63], v[144:147], v[184:187], v[60:63]
	v_mfma_f32_16x16x32_bf16 v[60:63], v[156:159], v[188:191], v[60:63]
	v_mfma_f32_16x16x32_bf16 v[52:55], v[156:159], v[196:199], v[52:55]
	v_mfma_f32_16x16x32_bf16 v[52:55], v[144:147], v[192:195], v[52:55]
	v_mfma_f32_16x16x32_bf16 v[36:39], v[144:147], v[200:203], v[36:39]
	v_mfma_f32_16x16x32_bf16 v[36:39], v[156:159], v[204:207], v[36:39]
	v_mfma_f32_16x16x32_bf16 v[20:23], v[156:159], v[212:215], v[20:23]
	v_mfma_f32_16x16x32_bf16 v[20:23], v[144:147], v[208:211], v[20:23]
	v_mfma_f32_16x16x32_bf16 v[12:15], v[160:163], v[208:211], v[12:15]
	v_mfma_f32_16x16x32_bf16 v[12:15], v[164:167], v[212:215], v[12:15]
	v_mfma_f32_16x16x32_bf16 v[28:31], v[164:167], v[204:207], v[28:31]
	v_mfma_f32_16x16x32_bf16 v[28:31], v[160:163], v[200:203], v[28:31]
	v_mfma_f32_16x16x32_bf16 v[44:47], v[160:163], v[192:195], v[44:47]
	v_mfma_f32_16x16x32_bf16 v[44:47], v[164:167], v[196:199], v[44:47]
	v_mfma_f32_16x16x32_bf16 v[56:59], v[164:167], v[188:191], v[56:59]
	v_mfma_f32_16x16x32_bf16 v[56:59], v[160:163], v[184:187], v[56:59]
	v_mfma_f32_16x16x32_bf16 v[48:51], v[168:171], v[184:187], v[48:51]
	v_mfma_f32_16x16x32_bf16 v[48:51], v[172:175], v[188:191], v[48:51]
	v_mfma_f32_16x16x32_bf16 v[32:35], v[172:175], v[196:199], v[32:35]
	v_mfma_f32_16x16x32_bf16 v[32:35], v[168:171], v[192:195], v[32:35]
	v_mfma_f32_16x16x32_bf16 v[16:19], v[168:171], v[200:203], v[16:19]
	v_mfma_f32_16x16x32_bf16 v[16:19], v[172:175], v[204:207], v[16:19]
	v_mfma_f32_16x16x32_bf16 v[4:7], v[172:175], v[212:215], v[4:7]
	v_mfma_f32_16x16x32_bf16 v[4:7], v[168:171], v[208:211], v[4:7]
	v_mfma_f32_16x16x32_bf16 v[0:3], v[176:179], v[208:211], v[0:3]
	v_mfma_f32_16x16x32_bf16 v[0:3], v[180:183], v[212:215], v[0:3]
	v_mfma_f32_16x16x32_bf16 v[8:11], v[180:183], v[204:207], v[8:11]
	v_mfma_f32_16x16x32_bf16 v[8:11], v[176:179], v[200:203], v[8:11]
	v_mfma_f32_16x16x32_bf16 v[24:27], v[176:179], v[192:195], v[24:27]
	v_mfma_f32_16x16x32_bf16 v[24:27], v[180:183], v[196:199], v[24:27]
	v_mfma_f32_16x16x32_bf16 v[40:43], v[180:183], v[188:191], v[40:43]
	v_mfma_f32_16x16x32_bf16 v[40:43], v[176:179], v[184:187], v[40:43]
	s_barrier
	s_add_i32 s56, s56, 2
	s_add_u32 s54, s54, 0x100
	s_addc_u32 s55, s55, 0
	s_cmp_gt_u32 s56, 61
	s_mov_b64 s[24:25], s[28:29]
	s_cbranch_scc0 .LBB0_333
	s_and_b64 vcc, exec, s[0:1]
	s_cbranch_vccz .LBB0_336
	s_barrier

.LBB0_1202:
	ds_read_b128 v[128:131], v176
	ds_read_b128 v[132:135], v176 offset:1024
	ds_read_b128 v[136:139], v176 offset:2048
	ds_read_b128 v[140:143], v176 offset:3072
	ds_read_b128 v[144:147], v177
	ds_read_b128 v[148:151], v177 offset:1024
	ds_read_b128 v[180:183], v177 offset:2048
	ds_read_b128 v[184:187], v177 offset:3072
	s_add_u32 s30, s28, 0xfff00080
	s_addc_u32 s31, s29, -1
	s_cmp_eq_u32 s40, 60
	s_cselect_b32 s35, s23, s31
	s_cselect_b32 s34, s36, s30
	s_cselect_b32 s31, s21, s39
	s_cselect_b32 s30, s37, s38
	v_lshl_add_u64 v[172:173], s[28:29], 0, v[164:165]
	s_add_i32 m0, s7, 0xc000
	s_nop 0
	global_load_lds_dwordx4 v[172:173], off
	v_lshl_add_u64 v[172:173], s[28:29], 0, v[166:167]
	s_add_i32 m0, s7, 0xe000
	s_nop 0
	global_load_lds_dwordx4 v[172:173], off
	ds_read_b128 v[188:191], v178
	ds_read_b128 v[192:195], v178 offset:1024
	ds_read_b128 v[196:199], v178 offset:2048
	ds_read_b128 v[200:203], v178 offset:3072
	ds_read_b128 v[204:207], v178 offset:4096
	ds_read_b128 v[208:211], v178 offset:5120
	ds_read_b128 v[212:215], v178 offset:6144
	ds_read_b128 v[216:219], v178 offset:7168
	s_waitcnt vmcnt(8)
	s_waitcnt lgkmcnt(0)
	s_barrier
	s_waitcnt lgkmcnt(0)
	v_mfma_f32_16x16x32_bf16 v[124:127], v[128:131], v[188:191], v[124:127]
	v_mfma_f32_16x16x32_bf16 v[124:127], v[132:135], v[192:195], v[124:127]
	v_mfma_f32_16x16x32_bf16 v[108:111], v[132:135], v[200:203], v[108:111]
	v_mfma_f32_16x16x32_bf16 v[108:111], v[128:131], v[196:199], v[108:111]
	v_mfma_f32_16x16x32_bf16 v[92:95], v[128:131], v[204:207], v[92:95]
	v_mfma_f32_16x16x32_bf16 v[92:95], v[132:135], v[208:211], v[92:95]
	v_mfma_f32_16x16x32_bf16 v[76:79], v[132:135], v[216:219], v[76:79]
	v_mfma_f32_16x16x32_bf16 v[76:79], v[128:131], v[212:215], v[76:79]
	v_mfma_f32_16x16x32_bf16 v[72:75], v[136:139], v[212:215], v[72:75]
	v_mfma_f32_16x16x32_bf16 v[72:75], v[140:143], v[216:219], v[72:75]
	v_mfma_f32_16x16x32_bf16 v[88:91], v[140:143], v[208:211], v[88:91]
	v_mfma_f32_16x16x32_bf16 v[88:91], v[136:139], v[204:207], v[88:91]
	v_mfma_f32_16x16x32_bf16 v[104:107], v[136:139], v[196:199], v[104:107]
	v_mfma_f32_16x16x32_bf16 v[104:107], v[140:143], v[200:203], v[104:107]
	v_mfma_f32_16x16x32_bf16 v[120:123], v[140:143], v[192:195], v[120:123]
	v_mfma_f32_16x16x32_bf16 v[120:123], v[136:139], v[188:191], v[120:123]
	v_mfma_f32_16x16x32_bf16 v[116:119], v[144:147], v[188:191], v[116:119]
	v_mfma_f32_16x16x32_bf16 v[116:119], v[148:151], v[192:195], v[116:119]
	v_mfma_f32_16x16x32_bf16 v[100:103], v[148:151], v[200:203], v[100:103]
	v_mfma_f32_16x16x32_bf16 v[100:103], v[144:147], v[196:199], v[100:103]
	v_mfma_f32_16x16x32_bf16 v[84:87], v[144:147], v[204:207], v[84:87]
	v_mfma_f32_16x16x32_bf16 v[84:87], v[148:151], v[208:211], v[84:87]
	v_mfma_f32_16x16x32_bf16 v[68:71], v[148:151], v[216:219], v[68:71]
	v_mfma_f32_16x16x32_bf16 v[68:71], v[144:147], v[212:215], v[68:71]
	v_mfma_f32_16x16x32_bf16 v[64:67], v[180:183], v[212:215], v[64:67]
	v_mfma_f32_16x16x32_bf16 v[64:67], v[184:187], v[216:219], v[64:67]
	v_mfma_f32_16x16x32_bf16 v[80:83], v[184:187], v[208:211], v[80:83]
	v_mfma_f32_16x16x32_bf16 v[80:83], v[180:183], v[204:207], v[80:83]
	v_mfma_f32_16x16x32_bf16 v[96:99], v[180:183], v[196:199], v[96:99]
	v_mfma_f32_16x16x32_bf16 v[96:99], v[184:187], v[200:203], v[96:99]
	v_mfma_f32_16x16x32_bf16 v[112:115], v[184:187], v[192:195], v[112:115]
	v_mfma_f32_16x16x32_bf16 v[112:115], v[180:183], v[188:191], v[112:115]
	s_barrier
	s_add_i32 s41, s68, s33
	v_lshl_add_u64 v[172:173], s[30:31], 0, v[154:155]
	s_mov_b32 m0, s41
	v_lshl_add_u64 v[220:221], s[30:31], 0, v[158:159]
	global_load_lds_dwordx4 v[172:173], off
	s_add_i32 m0, s41, 0x2000
	s_add_u32 s42, s30, 0x100000
	s_addc_u32 s43, s31, 0
	s_add_i32 s41, s69, s33
	global_load_lds_dwordx4 v[220:221], off
	v_lshl_add_u64 v[188:189], s[42:43], 0, v[154:155]
	s_mov_b32 m0, s41
	v_lshl_add_u64 v[222:223], s[34:35], 0, v[152:153]
	global_load_lds_dwordx4 v[188:189], off
	v_lshl_add_u64 v[188:189], s[42:43], 0, v[158:159]
	s_add_i32 m0, s41, 0x2000
	v_lshl_add_u64 v[224:225], s[34:35], 0, v[156:157]
	global_load_lds_dwordx4 v[188:189], off
	s_mov_b32 m0, s7
	s_nop 0
	global_load_lds_dwordx4 v[222:223], off
	s_mov_b32 m0, s59
	s_nop 0
	global_load_lds_dwordx4 v[224:225], off
	ds_read_b128 v[188:191], v178 offset:16384
	ds_read_b128 v[192:195], v178 offset:17408
	ds_read_b128 v[196:199], v178 offset:18432
	ds_read_b128 v[200:203], v178 offset:19456
	ds_read_b128 v[204:207], v178 offset:20480
	ds_read_b128 v[208:211], v178 offset:21504
	ds_read_b128 v[212:215], v178 offset:22528
	ds_read_b128 v[216:219], v178 offset:23552
	s_waitcnt vmcnt(8)
	s_waitcnt lgkmcnt(0)
	s_barrier
	s_waitcnt lgkmcnt(0)
	v_mfma_f32_16x16x32_bf16 v[60:63], v[128:131], v[188:191], v[60:63]
	v_mfma_f32_16x16x32_bf16 v[60:63], v[132:135], v[192:195], v[60:63]
	v_mfma_f32_16x16x32_bf16 v[44:47], v[132:135], v[200:203], v[44:47]
	v_mfma_f32_16x16x32_bf16 v[44:47], v[128:131], v[196:199], v[44:47]
	v_mfma_f32_16x16x32_bf16 v[28:31], v[128:131], v[204:207], v[28:31]
	v_mfma_f32_16x16x32_bf16 v[28:31], v[132:135], v[208:211], v[28:31]
	v_mfma_f32_16x16x32_bf16 v[12:15], v[132:135], v[216:219], v[12:15]
	v_mfma_f32_16x16x32_bf16 v[12:15], v[128:131], v[212:215], v[12:15]
	v_mfma_f32_16x16x32_bf16 v[8:11], v[136:139], v[212:215], v[8:11]
	v_mfma_f32_16x16x32_bf16 v[8:11], v[140:143], v[216:219], v[8:11]
	v_mfma_f32_16x16x32_bf16 v[24:27], v[140:143], v[208:211], v[24:27]
	v_mfma_f32_16x16x32_bf16 v[24:27], v[136:139], v[204:207], v[24:27]
	v_mfma_f32_16x16x32_bf16 v[40:43], v[136:139], v[196:199], v[40:43]
	v_mfma_f32_16x16x32_bf16 v[40:43], v[140:143], v[200:203], v[40:43]
	v_mfma_f32_16x16x32_bf16 v[56:59], v[140:143], v[192:195], v[56:59]
	v_mfma_f32_16x16x32_bf16 v[56:59], v[136:139], v[188:191], v[56:59]
	v_mfma_f32_16x16x32_bf16 v[52:55], v[144:147], v[188:191], v[52:55]
	v_mfma_f32_16x16x32_bf16 v[52:55], v[148:151], v[192:195], v[52:55]
	v_mfma_f32_16x16x32_bf16 v[36:39], v[148:151], v[200:203], v[36:39]
	v_mfma_f32_16x16x32_bf16 v[36:39], v[144:147], v[196:199], v[36:39]
	v_mfma_f32_16x16x32_bf16 v[20:23], v[144:147], v[204:207], v[20:23]
	v_mfma_f32_16x16x32_bf16 v[20:23], v[148:151], v[208:211], v[20:23]
	v_mfma_f32_16x16x32_bf16 v[4:7], v[148:151], v[216:219], v[4:7]
	v_mfma_f32_16x16x32_bf16 v[4:7], v[144:147], v[212:215], v[4:7]
	v_mfma_f32_16x16x32_bf16 v[0:3], v[180:183], v[212:215], v[0:3]
	v_mfma_f32_16x16x32_bf16 v[0:3], v[184:187], v[216:219], v[0:3]
	v_mfma_f32_16x16x32_bf16 v[16:19], v[184:187], v[208:211], v[16:19]
	v_mfma_f32_16x16x32_bf16 v[16:19], v[180:183], v[204:207], v[16:19]
	v_mfma_f32_16x16x32_bf16 v[32:35], v[180:183], v[196:199], v[32:35]
	v_mfma_f32_16x16x32_bf16 v[32:35], v[184:187], v[200:203], v[32:35]
	v_mfma_f32_16x16x32_bf16 v[48:51], v[184:187], v[192:195], v[48:51]
	v_mfma_f32_16x16x32_bf16 v[48:51], v[180:183], v[188:191], v[48:51]
	s_barrier
	s_add_i32 s41, 0, 0x18000
	s_add_i32 s42, 0, 0x1c000
	v_add_u32_e32 v140, s41, v174
	v_add_u32_e32 v184, s42, v174
	ds_read_b128 v[128:131], v140
	ds_read_b128 v[132:135], v140 offset:1024
	ds_read_b128 v[136:139], v140 offset:2048
	ds_read_b128 v[140:143], v140 offset:3072
	ds_read_b128 v[144:147], v184
	ds_read_b128 v[148:151], v184 offset:1024
	ds_read_b128 v[180:183], v184 offset:2048
	ds_read_b128 v[184:187], v184 offset:3072
	s_add_u32 s34, s34, 0x100000
	s_addc_u32 s35, s35, 0
	s_mov_b32 m0, s60
	v_lshl_add_u64 v[188:189], s[34:35], 0, v[152:153]
	global_load_lds_dwordx4 v[188:189], off
	v_lshl_add_u64 v[188:189], s[34:35], 0, v[156:157]
	s_mov_b32 m0, s61
	s_nop 0
	global_load_lds_dwordx4 v[188:189], off
	ds_read_b128 v[188:191], v178 offset:32768
	ds_read_b128 v[192:195], v178 offset:33792
	ds_read_b128 v[196:199], v178 offset:34816
	ds_read_b128 v[200:203], v178 offset:35840
	ds_read_b128 v[204:207], v178 offset:36864
	ds_read_b128 v[208:211], v178 offset:37888
	ds_read_b128 v[212:215], v178 offset:38912
	ds_read_b128 v[216:219], v178 offset:39936
	s_waitcnt vmcnt(8)
	s_waitcnt lgkmcnt(0)
	s_barrier
	s_waitcnt lgkmcnt(0)
	v_mfma_f32_16x16x32_bf16 v[124:127], v[128:131], v[188:191], v[124:127]
	v_mfma_f32_16x16x32_bf16 v[124:127], v[132:135], v[192:195], v[124:127]
	v_mfma_f32_16x16x32_bf16 v[108:111], v[132:135], v[200:203], v[108:111]
	v_mfma_f32_16x16x32_bf16 v[108:111], v[128:131], v[196:199], v[108:111]
	v_mfma_f32_16x16x32_bf16 v[92:95], v[128:131], v[204:207], v[92:95]
	v_mfma_f32_16x16x32_bf16 v[92:95], v[132:135], v[208:211], v[92:95]
	v_mfma_f32_16x16x32_bf16 v[76:79], v[132:135], v[216:219], v[76:79]
	v_mfma_f32_16x16x32_bf16 v[76:79], v[128:131], v[212:215], v[76:79]
	v_mfma_f32_16x16x32_bf16 v[72:75], v[136:139], v[212:215], v[72:75]
	v_mfma_f32_16x16x32_bf16 v[72:75], v[140:143], v[216:219], v[72:75]
	v_mfma_f32_16x16x32_bf16 v[88:91], v[140:143], v[208:211], v[88:91]
	v_mfma_f32_16x16x32_bf16 v[88:91], v[136:139], v[204:207], v[88:91]
	v_mfma_f32_16x16x32_bf16 v[104:107], v[136:139], v[196:199], v[104:107]
	v_mfma_f32_16x16x32_bf16 v[104:107], v[140:143], v[200:203], v[104:107]
	v_mfma_f32_16x16x32_bf16 v[120:123], v[140:143], v[192:195], v[120:123]
	v_mfma_f32_16x16x32_bf16 v[120:123], v[136:139], v[188:191], v[120:123]
	v_mfma_f32_16x16x32_bf16 v[116:119], v[144:147], v[188:191], v[116:119]
	v_mfma_f32_16x16x32_bf16 v[116:119], v[148:151], v[192:195], v[116:119]
	v_mfma_f32_16x16x32_bf16 v[100:103], v[148:151], v[200:203], v[100:103]
	v_mfma_f32_16x16x32_bf16 v[100:103], v[144:147], v[196:199], v[100:103]
	v_mfma_f32_16x16x32_bf16 v[84:87], v[144:147], v[204:207], v[84:87]
	v_mfma_f32_16x16x32_bf16 v[84:87], v[148:151], v[208:211], v[84:87]
	v_mfma_f32_16x16x32_bf16 v[68:71], v[148:151], v[216:219], v[68:71]
	v_mfma_f32_16x16x32_bf16 v[68:71], v[144:147], v[212:215], v[68:71]
	v_mfma_f32_16x16x32_bf16 v[64:67], v[180:183], v[212:215], v[64:67]
	v_mfma_f32_16x16x32_bf16 v[64:67], v[184:187], v[216:219], v[64:67]
	v_mfma_f32_16x16x32_bf16 v[80:83], v[184:187], v[208:211], v[80:83]
	v_mfma_f32_16x16x32_bf16 v[80:83], v[180:183], v[204:207], v[80:83]
	v_mfma_f32_16x16x32_bf16 v[96:99], v[180:183], v[196:199], v[96:99]
	v_mfma_f32_16x16x32_bf16 v[96:99], v[184:187], v[200:203], v[96:99]
	v_mfma_f32_16x16x32_bf16 v[112:115], v[184:187], v[192:195], v[112:115]
	v_mfma_f32_16x16x32_bf16 v[112:115], v[180:183], v[188:191], v[112:115]
	s_barrier
	s_add_i32 s34, s41, s33
	v_lshl_add_u64 v[172:173], v[172:173], 0, s[16:17]
	s_mov_b32 m0, s34
	s_nop 0
	global_load_lds_dwordx4 v[172:173], off
	s_add_i32 m0, s34, 0x2000
	s_add_u32 s30, s30, 0x100800
	v_lshl_add_u64 v[172:173], v[220:221], 0, s[16:17]
	s_addc_u32 s31, s31, 0
	s_add_i32 s34, s42, s33
	global_load_lds_dwordx4 v[172:173], off
	v_lshl_add_u64 v[172:173], s[30:31], 0, v[154:155]
	s_mov_b32 m0, s34
	s_nop 0
	global_load_lds_dwordx4 v[172:173], off
	v_lshl_add_u64 v[172:173], s[30:31], 0, v[158:159]
	s_add_i32 m0, s34, 0x2000
	s_nop 0
	global_load_lds_dwordx4 v[172:173], off
	v_lshl_add_u64 v[172:173], v[222:223], 0, s[18:19]
	s_mov_b32 m0, s63
	s_nop 0
	global_load_lds_dwordx4 v[172:173], off
	v_lshl_add_u64 v[172:173], v[224:225], 0, s[18:19]
	s_mov_b32 m0, s64
	s_nop 0
	global_load_lds_dwordx4 v[172:173], off
	ds_read_b128 v[188:191], v178 offset:49152
	ds_read_b128 v[192:195], v178 offset:50176
	ds_read_b128 v[196:199], v178 offset:51200
	ds_read_b128 v[200:203], v178 offset:52224
	ds_read_b128 v[204:207], v178 offset:53248
	ds_read_b128 v[208:211], v178 offset:54272
	ds_read_b128 v[212:215], v178 offset:55296
	ds_read_b128 v[216:219], v178 offset:56320
	s_waitcnt vmcnt(8)
	s_waitcnt lgkmcnt(0)
	s_barrier
	s_waitcnt lgkmcnt(0)
	v_mfma_f32_16x16x32_bf16 v[60:63], v[128:131], v[188:191], v[60:63]
	v_mfma_f32_16x16x32_bf16 v[60:63], v[132:135], v[192:195], v[60:63]
	v_mfma_f32_16x16x32_bf16 v[44:47], v[132:135], v[200:203], v[44:47]
	v_mfma_f32_16x16x32_bf16 v[44:47], v[128:131], v[196:199], v[44:47]
	v_mfma_f32_16x16x32_bf16 v[28:31], v[128:131], v[204:207], v[28:31]
	v_mfma_f32_16x16x32_bf16 v[28:31], v[132:135], v[208:211], v[28:31]
	v_mfma_f32_16x16x32_bf16 v[12:15], v[132:135], v[216:219], v[12:15]
	v_mfma_f32_16x16x32_bf16 v[12:15], v[128:131], v[212:215], v[12:15]
	v_mfma_f32_16x16x32_bf16 v[8:11], v[136:139], v[212:215], v[8:11]
	v_mfma_f32_16x16x32_bf16 v[8:11], v[140:143], v[216:219], v[8:11]
	v_mfma_f32_16x16x32_bf16 v[24:27], v[140:143], v[208:211], v[24:27]
	v_mfma_f32_16x16x32_bf16 v[24:27], v[136:139], v[204:207], v[24:27]
	v_mfma_f32_16x16x32_bf16 v[40:43], v[136:139], v[196:199], v[40:43]
	v_mfma_f32_16x16x32_bf16 v[40:43], v[140:143], v[200:203], v[40:43]
	v_mfma_f32_16x16x32_bf16 v[56:59], v[140:143], v[192:195], v[56:59]
	v_mfma_f32_16x16x32_bf16 v[56:59], v[136:139], v[188:191], v[56:59]
	v_mfma_f32_16x16x32_bf16 v[52:55], v[144:147], v[188:191], v[52:55]
	v_mfma_f32_16x16x32_bf16 v[52:55], v[148:151], v[192:195], v[52:55]
	v_mfma_f32_16x16x32_bf16 v[36:39], v[148:151], v[200:203], v[36:39]
	v_mfma_f32_16x16x32_bf16 v[36:39], v[144:147], v[196:199], v[36:39]
	v_mfma_f32_16x16x32_bf16 v[20:23], v[144:147], v[204:207], v[20:23]
	v_mfma_f32_16x16x32_bf16 v[20:23], v[148:151], v[208:211], v[20:23]
	v_mfma_f32_16x16x32_bf16 v[4:7], v[148:151], v[216:219], v[4:7]
	v_mfma_f32_16x16x32_bf16 v[4:7], v[144:147], v[212:215], v[4:7]
	v_mfma_f32_16x16x32_bf16 v[0:3], v[180:183], v[212:215], v[0:3]
	v_mfma_f32_16x16x32_bf16 v[0:3], v[184:187], v[216:219], v[0:3]
	v_mfma_f32_16x16x32_bf16 v[16:19], v[184:187], v[208:211], v[16:19]
	v_mfma_f32_16x16x32_bf16 v[16:19], v[180:183], v[204:207], v[16:19]
	v_mfma_f32_16x16x32_bf16 v[32:35], v[180:183], v[196:199], v[32:35]
	v_mfma_f32_16x16x32_bf16 v[32:35], v[184:187], v[200:203], v[32:35]
	v_mfma_f32_16x16x32_bf16 v[48:51], v[184:187], v[192:195], v[48:51]
	v_mfma_f32_16x16x32_bf16 v[48:51], v[180:183], v[188:191], v[48:51]
	s_barrier
	s_add_i32 s40, s40, 2
	s_add_u32 s38, s38, 0x1000
	s_addc_u32 s39, s39, 0
	s_add_u32 s28, s28, 0x100
	s_addc_u32 s29, s29, 0
	s_cmp_gt_u32 s40, 61
	s_cbranch_scc0 .LBB0_1202
	s_and_b64 vcc, exec, s[10:11]
	s_cbranch_vccz .LBB0_1205
	s_barrier

.LBB0_1263:
	ds_read_b128 v[146:149], v152
	ds_read_b128 v[156:159], v152 offset:1024
	ds_read_b128 v[160:163], v152 offset:2048
	ds_read_b128 v[164:167], v152 offset:3072
	ds_read_b128 v[168:171], v153
	ds_read_b128 v[172:175], v153 offset:1024
	ds_read_b128 v[176:179], v153 offset:2048
	ds_read_b128 v[180:183], v153 offset:3072
	s_add_u32 s22, s20, 0x100
	s_addc_u32 s23, s21, 0
	s_cmp_eq_u32 s46, 12
	s_cselect_b32 s27, s5, s23
	s_cselect_b32 s26, s4, s22
	s_cselect_b32 s25, s19, s15
	s_cselect_b32 s24, s18, s6
	v_lshl_add_u64 v[184:185], s[20:21], 0, v[136:137]
	s_add_i32 m0, s17, 0xc000
	s_nop 0
	global_load_lds_dwordx4 v[184:185], off
	v_lshl_add_u64 v[184:185], s[20:21], 0, v[138:139]
	s_add_i32 m0, s17, 0xe000
	s_nop 0
	global_load_lds_dwordx4 v[184:185], off
	ds_read_b128 v[184:187], v154
	ds_read_b128 v[188:191], v154 offset:1024
	ds_read_b128 v[192:195], v154 offset:2048
	ds_read_b128 v[196:199], v154 offset:3072
	ds_read_b128 v[200:203], v154 offset:4096
	ds_read_b128 v[204:207], v154 offset:5120
	ds_read_b128 v[208:211], v154 offset:6144
	ds_read_b128 v[212:215], v154 offset:7168
	s_waitcnt vmcnt(8)
	s_waitcnt lgkmcnt(0)
	s_barrier
	s_waitcnt lgkmcnt(0)
	v_mfma_f32_16x16x32_bf16 v[124:127], v[146:149], v[184:187], v[124:127]
	v_mfma_f32_16x16x32_bf16 v[124:127], v[156:159], v[188:191], v[124:127]
	v_mfma_f32_16x16x32_bf16 v[112:115], v[156:159], v[196:199], v[112:115]
	v_mfma_f32_16x16x32_bf16 v[112:115], v[146:149], v[192:195], v[112:115]
	v_mfma_f32_16x16x32_bf16 v[96:99], v[146:149], v[200:203], v[96:99]
	v_mfma_f32_16x16x32_bf16 v[96:99], v[156:159], v[204:207], v[96:99]
	v_mfma_f32_16x16x32_bf16 v[80:83], v[156:159], v[212:215], v[80:83]
	v_mfma_f32_16x16x32_bf16 v[80:83], v[146:149], v[208:211], v[80:83]
	v_mfma_f32_16x16x32_bf16 v[72:75], v[160:163], v[208:211], v[72:75]
	v_mfma_f32_16x16x32_bf16 v[72:75], v[164:167], v[212:215], v[72:75]
	v_mfma_f32_16x16x32_bf16 v[88:91], v[164:167], v[204:207], v[88:91]
	v_mfma_f32_16x16x32_bf16 v[88:91], v[160:163], v[200:203], v[88:91]
	v_mfma_f32_16x16x32_bf16 v[104:107], v[160:163], v[192:195], v[104:107]
	v_mfma_f32_16x16x32_bf16 v[104:107], v[164:167], v[196:199], v[104:107]
	v_mfma_f32_16x16x32_bf16 v[120:123], v[164:167], v[188:191], v[120:123]
	v_mfma_f32_16x16x32_bf16 v[120:123], v[160:163], v[184:187], v[120:123]
	v_mfma_f32_16x16x32_bf16 v[116:119], v[168:171], v[184:187], v[116:119]
	v_mfma_f32_16x16x32_bf16 v[116:119], v[172:175], v[188:191], v[116:119]
	v_mfma_f32_16x16x32_bf16 v[100:103], v[172:175], v[196:199], v[100:103]
	v_mfma_f32_16x16x32_bf16 v[100:103], v[168:171], v[192:195], v[100:103]
	v_mfma_f32_16x16x32_bf16 v[84:87], v[168:171], v[200:203], v[84:87]
	v_mfma_f32_16x16x32_bf16 v[84:87], v[172:175], v[204:207], v[84:87]
	v_mfma_f32_16x16x32_bf16 v[68:71], v[172:175], v[212:215], v[68:71]
	v_mfma_f32_16x16x32_bf16 v[68:71], v[168:171], v[208:211], v[68:71]
	v_mfma_f32_16x16x32_bf16 v[64:67], v[176:179], v[208:211], v[64:67]
	v_mfma_f32_16x16x32_bf16 v[64:67], v[180:183], v[212:215], v[64:67]
	v_mfma_f32_16x16x32_bf16 v[76:79], v[180:183], v[204:207], v[76:79]
	v_mfma_f32_16x16x32_bf16 v[76:79], v[176:179], v[200:203], v[76:79]
	v_mfma_f32_16x16x32_bf16 v[92:95], v[176:179], v[192:195], v[92:95]
	v_mfma_f32_16x16x32_bf16 v[92:95], v[180:183], v[196:199], v[92:95]
	v_mfma_f32_16x16x32_bf16 v[108:111], v[180:183], v[188:191], v[108:111]
	v_mfma_f32_16x16x32_bf16 v[108:111], v[176:179], v[184:187], v[108:111]
	s_barrier
	s_add_i32 s20, s41, s33
	v_lshl_add_u64 v[216:217], s[24:25], 0, v[130:131]
	s_mov_b32 m0, s20
	v_lshl_add_u64 v[218:219], s[24:25], 0, v[134:135]
	global_load_lds_dwordx4 v[216:217], off
	s_add_i32 m0, s20, 0x2000
	s_add_u32 s20, s24, 0x200000
	s_addc_u32 s21, s25, 0
	s_add_i32 s47, s42, s33
	global_load_lds_dwordx4 v[218:219], off
	v_lshl_add_u64 v[184:185], s[20:21], 0, v[130:131]
	s_mov_b32 m0, s47
	v_lshl_add_u64 v[220:221], s[26:27], 0, v[128:129]
	global_load_lds_dwordx4 v[184:185], off
	v_lshl_add_u64 v[184:185], s[20:21], 0, v[134:135]
	s_add_i32 m0, s47, 0x2000
	v_lshl_add_u64 v[222:223], s[26:27], 0, v[132:133]
	global_load_lds_dwordx4 v[184:185], off
	s_mov_b32 m0, s17
	s_nop 0
	global_load_lds_dwordx4 v[220:221], off
	s_mov_b32 m0, s34
	s_nop 0
	global_load_lds_dwordx4 v[222:223], off
	ds_read_b128 v[184:187], v154 offset:16384
	ds_read_b128 v[188:191], v154 offset:17408
	ds_read_b128 v[192:195], v154 offset:18432
	ds_read_b128 v[196:199], v154 offset:19456
	ds_read_b128 v[200:203], v154 offset:20480
	ds_read_b128 v[204:207], v154 offset:21504
	ds_read_b128 v[208:211], v154 offset:22528
	ds_read_b128 v[212:215], v154 offset:23552
	s_waitcnt vmcnt(8)
	s_waitcnt lgkmcnt(0)
	s_barrier
	s_waitcnt lgkmcnt(0)
	v_mfma_f32_16x16x32_bf16 v[60:63], v[146:149], v[184:187], v[60:63]
	v_mfma_f32_16x16x32_bf16 v[60:63], v[156:159], v[188:191], v[60:63]
	v_mfma_f32_16x16x32_bf16 v[48:51], v[156:159], v[196:199], v[48:51]
	v_mfma_f32_16x16x32_bf16 v[48:51], v[146:149], v[192:195], v[48:51]
	v_mfma_f32_16x16x32_bf16 v[32:35], v[146:149], v[200:203], v[32:35]
	v_mfma_f32_16x16x32_bf16 v[32:35], v[156:159], v[204:207], v[32:35]
	v_mfma_f32_16x16x32_bf16 v[16:19], v[156:159], v[212:215], v[16:19]
	v_mfma_f32_16x16x32_bf16 v[16:19], v[146:149], v[208:211], v[16:19]
	v_mfma_f32_16x16x32_bf16 v[8:11], v[160:163], v[208:211], v[8:11]
	v_mfma_f32_16x16x32_bf16 v[8:11], v[164:167], v[212:215], v[8:11]
	v_mfma_f32_16x16x32_bf16 v[24:27], v[164:167], v[204:207], v[24:27]
	v_mfma_f32_16x16x32_bf16 v[24:27], v[160:163], v[200:203], v[24:27]
	v_mfma_f32_16x16x32_bf16 v[40:43], v[160:163], v[192:195], v[40:43]
	v_mfma_f32_16x16x32_bf16 v[40:43], v[164:167], v[196:199], v[40:43]
	v_mfma_f32_16x16x32_bf16 v[56:59], v[164:167], v[188:191], v[56:59]
	v_mfma_f32_16x16x32_bf16 v[56:59], v[160:163], v[184:187], v[56:59]
	v_mfma_f32_16x16x32_bf16 v[52:55], v[168:171], v[184:187], v[52:55]
	v_mfma_f32_16x16x32_bf16 v[52:55], v[172:175], v[188:191], v[52:55]
	v_mfma_f32_16x16x32_bf16 v[36:39], v[172:175], v[196:199], v[36:39]
	v_mfma_f32_16x16x32_bf16 v[36:39], v[168:171], v[192:195], v[36:39]
	v_mfma_f32_16x16x32_bf16 v[20:23], v[168:171], v[200:203], v[20:23]
	v_mfma_f32_16x16x32_bf16 v[20:23], v[172:175], v[204:207], v[20:23]
	v_mfma_f32_16x16x32_bf16 v[4:7], v[172:175], v[212:215], v[4:7]
	v_mfma_f32_16x16x32_bf16 v[4:7], v[168:171], v[208:211], v[4:7]
	v_mfma_f32_16x16x32_bf16 v[0:3], v[176:179], v[208:211], v[0:3]
	v_mfma_f32_16x16x32_bf16 v[0:3], v[180:183], v[212:215], v[0:3]
	v_mfma_f32_16x16x32_bf16 v[12:15], v[180:183], v[204:207], v[12:15]
	v_mfma_f32_16x16x32_bf16 v[12:15], v[176:179], v[200:203], v[12:15]
	v_mfma_f32_16x16x32_bf16 v[28:31], v[176:179], v[192:195], v[28:31]
	v_mfma_f32_16x16x32_bf16 v[28:31], v[180:183], v[196:199], v[28:31]
	v_mfma_f32_16x16x32_bf16 v[44:47], v[180:183], v[188:191], v[44:47]
	v_mfma_f32_16x16x32_bf16 v[44:47], v[176:179], v[184:187], v[44:47]
	s_barrier
	s_add_i32 s47, 0, 0x18000
	v_add_u32_e32 v144, s47, v145
	s_add_i32 s48, 0, 0x1c000
	ds_read_b128 v[146:149], v144
	ds_read_b128 v[156:159], v144 offset:1024
	ds_read_b128 v[160:163], v144 offset:2048
	ds_read_b128 v[164:167], v144 offset:3072
	v_add_u32_e32 v144, s48, v145
	ds_read_b128 v[168:171], v144
	ds_read_b128 v[172:175], v144 offset:1024
	ds_read_b128 v[176:179], v144 offset:2048
	ds_read_b128 v[180:183], v144 offset:3072
	s_add_u32 s20, s26, 0x200000
	s_addc_u32 s21, s27, 0
	s_mov_b32 m0, s35
	v_lshl_add_u64 v[184:185], s[20:21], 0, v[128:129]
	global_load_lds_dwordx4 v[184:185], off
	v_lshl_add_u64 v[184:185], s[20:21], 0, v[132:133]
	s_mov_b32 m0, s36
	s_nop 0
	global_load_lds_dwordx4 v[184:185], off
	ds_read_b128 v[184:187], v154 offset:32768
	ds_read_b128 v[188:191], v154 offset:33792
	ds_read_b128 v[192:195], v154 offset:34816
	ds_read_b128 v[196:199], v154 offset:35840
	ds_read_b128 v[200:203], v154 offset:36864
	ds_read_b128 v[204:207], v154 offset:37888
	ds_read_b128 v[208:211], v154 offset:38912
	ds_read_b128 v[212:215], v154 offset:39936
	s_waitcnt vmcnt(8)
	s_waitcnt lgkmcnt(0)
	s_barrier
	s_waitcnt lgkmcnt(0)
	v_mfma_f32_16x16x32_bf16 v[124:127], v[146:149], v[184:187], v[124:127]
	v_mfma_f32_16x16x32_bf16 v[124:127], v[156:159], v[188:191], v[124:127]
	v_mfma_f32_16x16x32_bf16 v[112:115], v[156:159], v[196:199], v[112:115]
	v_mfma_f32_16x16x32_bf16 v[112:115], v[146:149], v[192:195], v[112:115]
	v_mfma_f32_16x16x32_bf16 v[96:99], v[146:149], v[200:203], v[96:99]
	v_mfma_f32_16x16x32_bf16 v[96:99], v[156:159], v[204:207], v[96:99]
	v_mfma_f32_16x16x32_bf16 v[80:83], v[156:159], v[212:215], v[80:83]
	v_mfma_f32_16x16x32_bf16 v[80:83], v[146:149], v[208:211], v[80:83]
	v_mfma_f32_16x16x32_bf16 v[72:75], v[160:163], v[208:211], v[72:75]
	v_mfma_f32_16x16x32_bf16 v[72:75], v[164:167], v[212:215], v[72:75]
	v_mfma_f32_16x16x32_bf16 v[88:91], v[164:167], v[204:207], v[88:91]
	v_mfma_f32_16x16x32_bf16 v[88:91], v[160:163], v[200:203], v[88:91]
	v_mfma_f32_16x16x32_bf16 v[104:107], v[160:163], v[192:195], v[104:107]
	v_mfma_f32_16x16x32_bf16 v[104:107], v[164:167], v[196:199], v[104:107]
	v_mfma_f32_16x16x32_bf16 v[120:123], v[164:167], v[188:191], v[120:123]
	v_mfma_f32_16x16x32_bf16 v[120:123], v[160:163], v[184:187], v[120:123]
	v_mfma_f32_16x16x32_bf16 v[116:119], v[168:171], v[184:187], v[116:119]
	v_mfma_f32_16x16x32_bf16 v[116:119], v[172:175], v[188:191], v[116:119]
	v_mfma_f32_16x16x32_bf16 v[100:103], v[172:175], v[196:199], v[100:103]
	v_mfma_f32_16x16x32_bf16 v[100:103], v[168:171], v[192:195], v[100:103]
	v_mfma_f32_16x16x32_bf16 v[84:87], v[168:171], v[200:203], v[84:87]
	v_mfma_f32_16x16x32_bf16 v[84:87], v[172:175], v[204:207], v[84:87]
	v_mfma_f32_16x16x32_bf16 v[68:71], v[172:175], v[212:215], v[68:71]
	v_mfma_f32_16x16x32_bf16 v[68:71], v[168:171], v[208:211], v[68:71]
	v_mfma_f32_16x16x32_bf16 v[64:67], v[176:179], v[208:211], v[64:67]
	v_mfma_f32_16x16x32_bf16 v[64:67], v[180:183], v[212:215], v[64:67]
	v_mfma_f32_16x16x32_bf16 v[76:79], v[180:183], v[204:207], v[76:79]
	v_mfma_f32_16x16x32_bf16 v[76:79], v[176:179], v[200:203], v[76:79]
	v_mfma_f32_16x16x32_bf16 v[92:95], v[176:179], v[192:195], v[92:95]
	v_mfma_f32_16x16x32_bf16 v[92:95], v[180:183], v[196:199], v[92:95]
	v_mfma_f32_16x16x32_bf16 v[108:111], v[180:183], v[188:191], v[108:111]
	v_mfma_f32_16x16x32_bf16 v[108:111], v[176:179], v[184:187], v[108:111]
	s_barrier
	s_add_i32 s20, s47, s33
	v_lshl_add_u64 v[184:185], v[216:217], 0, s[12:13]
	s_mov_b32 m0, s20
	s_nop 0
	global_load_lds_dwordx4 v[184:185], off
	s_add_i32 m0, s20, 0x2000
	s_add_u32 s20, s24, 0x200080
	v_lshl_add_u64 v[184:185], v[218:219], 0, s[12:13]
	s_addc_u32 s21, s25, 0
	s_add_i32 s24, s48, s33
	global_load_lds_dwordx4 v[184:185], off
	v_lshl_add_u64 v[184:185], s[20:21], 0, v[130:131]
	s_mov_b32 m0, s24
	s_nop 0
	global_load_lds_dwordx4 v[184:185], off
	v_lshl_add_u64 v[184:185], s[20:21], 0, v[134:135]
	s_add_i32 m0, s24, 0x2000
	s_nop 0
	global_load_lds_dwordx4 v[184:185], off
	v_lshl_add_u64 v[184:185], v[220:221], 0, s[12:13]
	s_mov_b32 m0, s37
	s_nop 0
	global_load_lds_dwordx4 v[184:185], off
	v_lshl_add_u64 v[184:185], v[222:223], 0, s[12:13]
	s_mov_b32 m0, s38
	s_nop 0
	global_load_lds_dwordx4 v[184:185], off
	ds_read_b128 v[184:187], v154 offset:49152
	ds_read_b128 v[188:191], v154 offset:50176
	ds_read_b128 v[192:195], v154 offset:51200
	ds_read_b128 v[196:199], v154 offset:52224
	ds_read_b128 v[200:203], v154 offset:53248
	ds_read_b128 v[204:207], v154 offset:54272
	ds_read_b128 v[208:211], v154 offset:55296
	ds_read_b128 v[212:215], v154 offset:56320
	s_waitcnt vmcnt(8)
	s_waitcnt lgkmcnt(0)
	s_barrier
	s_waitcnt lgkmcnt(0)
	v_mfma_f32_16x16x32_bf16 v[60:63], v[146:149], v[184:187], v[60:63]
	v_mfma_f32_16x16x32_bf16 v[60:63], v[156:159], v[188:191], v[60:63]
	v_mfma_f32_16x16x32_bf16 v[48:51], v[156:159], v[196:199], v[48:51]
	v_mfma_f32_16x16x32_bf16 v[48:51], v[146:149], v[192:195], v[48:51]
	v_mfma_f32_16x16x32_bf16 v[32:35], v[146:149], v[200:203], v[32:35]
	v_mfma_f32_16x16x32_bf16 v[32:35], v[156:159], v[204:207], v[32:35]
	v_mfma_f32_16x16x32_bf16 v[16:19], v[156:159], v[212:215], v[16:19]
	v_mfma_f32_16x16x32_bf16 v[16:19], v[146:149], v[208:211], v[16:19]
	v_mfma_f32_16x16x32_bf16 v[8:11], v[160:163], v[208:211], v[8:11]
	v_mfma_f32_16x16x32_bf16 v[8:11], v[164:167], v[212:215], v[8:11]
	v_mfma_f32_16x16x32_bf16 v[24:27], v[164:167], v[204:207], v[24:27]
	v_mfma_f32_16x16x32_bf16 v[24:27], v[160:163], v[200:203], v[24:27]
	v_mfma_f32_16x16x32_bf16 v[40:43], v[160:163], v[192:195], v[40:43]
	v_mfma_f32_16x16x32_bf16 v[40:43], v[164:167], v[196:199], v[40:43]
	v_mfma_f32_16x16x32_bf16 v[56:59], v[164:167], v[188:191], v[56:59]
	v_mfma_f32_16x16x32_bf16 v[56:59], v[160:163], v[184:187], v[56:59]
	v_mfma_f32_16x16x32_bf16 v[52:55], v[168:171], v[184:187], v[52:55]
	v_mfma_f32_16x16x32_bf16 v[52:55], v[172:175], v[188:191], v[52:55]
	v_mfma_f32_16x16x32_bf16 v[36:39], v[172:175], v[196:199], v[36:39]
	v_mfma_f32_16x16x32_bf16 v[36:39], v[168:171], v[192:195], v[36:39]
	v_mfma_f32_16x16x32_bf16 v[20:23], v[168:171], v[200:203], v[20:23]
	v_mfma_f32_16x16x32_bf16 v[20:23], v[172:175], v[204:207], v[20:23]
	v_mfma_f32_16x16x32_bf16 v[4:7], v[172:175], v[212:215], v[4:7]
	v_mfma_f32_16x16x32_bf16 v[4:7], v[168:171], v[208:211], v[4:7]
	v_mfma_f32_16x16x32_bf16 v[0:3], v[176:179], v[208:211], v[0:3]
	v_mfma_f32_16x16x32_bf16 v[0:3], v[180:183], v[212:215], v[0:3]
	v_mfma_f32_16x16x32_bf16 v[12:15], v[180:183], v[204:207], v[12:15]
	v_mfma_f32_16x16x32_bf16 v[12:15], v[176:179], v[200:203], v[12:15]
	v_mfma_f32_16x16x32_bf16 v[28:31], v[176:179], v[192:195], v[28:31]
	v_mfma_f32_16x16x32_bf16 v[28:31], v[180:183], v[196:199], v[28:31]
	v_mfma_f32_16x16x32_bf16 v[44:47], v[180:183], v[188:191], v[44:47]
	v_mfma_f32_16x16x32_bf16 v[44:47], v[176:179], v[184:187], v[44:47]
	s_barrier
	s_add_i32 s46, s46, 2
	s_add_u32 s6, s6, 0x100
	s_addc_u32 s15, s15, 0
	s_cmp_gt_u32 s46, 13
	s_mov_b64 s[20:21], s[22:23]
	s_cbranch_scc0 .LBB0_1263
	s_and_b64 vcc, exec, s[8:9]
	s_cbranch_vccz .LBB0_1266
	s_barrier

.LBB0_1340:
	v_add_u32_e32 v166, s51, v152
	v_add_u32_e32 v182, s52, v152
	ds_read_b128 v[154:157], v166
	ds_read_b128 v[158:161], v166 offset:1024
	ds_read_b128 v[162:165], v166 offset:2048
	ds_read_b128 v[166:169], v166 offset:3072
	ds_read_b128 v[170:173], v182
	ds_read_b128 v[174:177], v182 offset:1024
	ds_read_b128 v[178:181], v182 offset:2048
	ds_read_b128 v[182:185], v182 offset:3072
	s_add_u32 s30, s10, s28
	s_addc_u32 s31, s11, s29
	s_cmp_eq_u32 s58, 60
	s_cselect_b32 s35, s23, s31
	s_cselect_b32 s34, s54, s30
	s_cselect_b32 s31, s21, s57
	s_cselect_b32 s30, s55, s56
	v_lshl_add_u64 v[186:187], s[10:11], 0, v[146:147]
	s_add_i32 m0, s44, 0xc000
	s_nop 0
	global_load_lds_dwordx4 v[186:187], off
	v_lshl_add_u64 v[186:187], s[10:11], 0, v[144:145]
	s_add_i32 m0, s44, 0xe000
	s_nop 0
	global_load_lds_dwordx4 v[186:187], off
	ds_read_b128 v[186:189], v153
	ds_read_b128 v[190:193], v153 offset:1024
	ds_read_b128 v[194:197], v153 offset:2048
	ds_read_b128 v[198:201], v153 offset:3072
	ds_read_b128 v[202:205], v153 offset:4096
	ds_read_b128 v[206:209], v153 offset:5120
	ds_read_b128 v[210:213], v153 offset:6144
	ds_read_b128 v[214:217], v153 offset:7168
	s_waitcnt vmcnt(8)
	s_waitcnt lgkmcnt(0)
	s_barrier
	s_waitcnt lgkmcnt(0)
	v_mfma_f32_16x16x32_bf16 v[124:127], v[154:157], v[186:189], v[124:127]
	v_mfma_f32_16x16x32_bf16 v[124:127], v[158:161], v[190:193], v[124:127]
	v_mfma_f32_16x16x32_bf16 v[108:111], v[158:161], v[198:201], v[108:111]
	v_mfma_f32_16x16x32_bf16 v[108:111], v[154:157], v[194:197], v[108:111]
	v_mfma_f32_16x16x32_bf16 v[92:95], v[154:157], v[202:205], v[92:95]
	v_mfma_f32_16x16x32_bf16 v[92:95], v[158:161], v[206:209], v[92:95]
	v_mfma_f32_16x16x32_bf16 v[76:79], v[158:161], v[214:217], v[76:79]
	v_mfma_f32_16x16x32_bf16 v[76:79], v[154:157], v[210:213], v[76:79]
	v_mfma_f32_16x16x32_bf16 v[72:75], v[162:165], v[210:213], v[72:75]
	v_mfma_f32_16x16x32_bf16 v[72:75], v[166:169], v[214:217], v[72:75]
	v_mfma_f32_16x16x32_bf16 v[88:91], v[166:169], v[206:209], v[88:91]
	v_mfma_f32_16x16x32_bf16 v[88:91], v[162:165], v[202:205], v[88:91]
	v_mfma_f32_16x16x32_bf16 v[104:107], v[162:165], v[194:197], v[104:107]
	v_mfma_f32_16x16x32_bf16 v[104:107], v[166:169], v[198:201], v[104:107]
	v_mfma_f32_16x16x32_bf16 v[120:123], v[166:169], v[190:193], v[120:123]
	v_mfma_f32_16x16x32_bf16 v[120:123], v[162:165], v[186:189], v[120:123]
	v_mfma_f32_16x16x32_bf16 v[116:119], v[170:173], v[186:189], v[116:119]
	v_mfma_f32_16x16x32_bf16 v[116:119], v[174:177], v[190:193], v[116:119]
	v_mfma_f32_16x16x32_bf16 v[100:103], v[174:177], v[198:201], v[100:103]
	v_mfma_f32_16x16x32_bf16 v[100:103], v[170:173], v[194:197], v[100:103]
	v_mfma_f32_16x16x32_bf16 v[84:87], v[170:173], v[202:205], v[84:87]
	v_mfma_f32_16x16x32_bf16 v[84:87], v[174:177], v[206:209], v[84:87]
	v_mfma_f32_16x16x32_bf16 v[68:71], v[174:177], v[214:217], v[68:71]
	v_mfma_f32_16x16x32_bf16 v[68:71], v[170:173], v[210:213], v[68:71]
	v_mfma_f32_16x16x32_bf16 v[64:67], v[178:181], v[210:213], v[64:67]
	v_mfma_f32_16x16x32_bf16 v[64:67], v[182:185], v[214:217], v[64:67]
	v_mfma_f32_16x16x32_bf16 v[80:83], v[182:185], v[206:209], v[80:83]
	v_mfma_f32_16x16x32_bf16 v[80:83], v[178:181], v[202:205], v[80:83]
	v_mfma_f32_16x16x32_bf16 v[96:99], v[178:181], v[194:197], v[96:99]
	v_mfma_f32_16x16x32_bf16 v[96:99], v[182:185], v[198:201], v[96:99]
	v_mfma_f32_16x16x32_bf16 v[112:115], v[182:185], v[190:193], v[112:115]
	v_mfma_f32_16x16x32_bf16 v[112:115], v[178:181], v[186:189], v[112:115]
	s_barrier
	s_add_i32 s59, s51, s43
	v_lshl_add_u64 v[218:219], s[30:31], 0, v[130:131]
	s_mov_b32 m0, s59
	v_lshl_add_u64 v[220:221], s[30:31], 0, v[134:135]
	global_load_lds_dwordx4 v[218:219], off
	s_add_i32 m0, s59, 0x2000
	s_add_u32 s60, s30, 0x100000
	s_addc_u32 s61, s31, 0
	s_add_i32 s59, s52, s43
	global_load_lds_dwordx4 v[220:221], off
	v_lshl_add_u64 v[186:187], s[60:61], 0, v[130:131]
	s_mov_b32 m0, s59
	v_lshl_add_u64 v[222:223], s[34:35], 0, v[128:129]
	global_load_lds_dwordx4 v[186:187], off
	v_lshl_add_u64 v[186:187], s[60:61], 0, v[134:135]
	s_add_i32 m0, s59, 0x2000
	v_lshl_add_u64 v[224:225], s[34:35], 0, v[132:133]
	global_load_lds_dwordx4 v[186:187], off
	s_mov_b32 m0, s44
	s_nop 0
	global_load_lds_dwordx4 v[222:223], off
	s_mov_b32 m0, s45
	s_nop 0
	global_load_lds_dwordx4 v[224:225], off
	ds_read_b128 v[186:189], v153 offset:16384
	ds_read_b128 v[190:193], v153 offset:17408
	ds_read_b128 v[194:197], v153 offset:18432
	ds_read_b128 v[198:201], v153 offset:19456
	ds_read_b128 v[202:205], v153 offset:20480
	ds_read_b128 v[206:209], v153 offset:21504
	ds_read_b128 v[210:213], v153 offset:22528
	ds_read_b128 v[214:217], v153 offset:23552
	s_waitcnt vmcnt(8)
	s_waitcnt lgkmcnt(0)
	s_barrier
	s_waitcnt lgkmcnt(0)
	v_mfma_f32_16x16x32_bf16 v[60:63], v[154:157], v[186:189], v[60:63]
	v_mfma_f32_16x16x32_bf16 v[60:63], v[158:161], v[190:193], v[60:63]
	v_mfma_f32_16x16x32_bf16 v[44:47], v[158:161], v[198:201], v[44:47]
	v_mfma_f32_16x16x32_bf16 v[44:47], v[154:157], v[194:197], v[44:47]
	v_mfma_f32_16x16x32_bf16 v[28:31], v[154:157], v[202:205], v[28:31]
	v_mfma_f32_16x16x32_bf16 v[28:31], v[158:161], v[206:209], v[28:31]
	v_mfma_f32_16x16x32_bf16 v[12:15], v[158:161], v[214:217], v[12:15]
	v_mfma_f32_16x16x32_bf16 v[12:15], v[154:157], v[210:213], v[12:15]
	v_mfma_f32_16x16x32_bf16 v[8:11], v[162:165], v[210:213], v[8:11]
	v_mfma_f32_16x16x32_bf16 v[8:11], v[166:169], v[214:217], v[8:11]
	v_mfma_f32_16x16x32_bf16 v[24:27], v[166:169], v[206:209], v[24:27]
	v_mfma_f32_16x16x32_bf16 v[24:27], v[162:165], v[202:205], v[24:27]
	v_mfma_f32_16x16x32_bf16 v[40:43], v[162:165], v[194:197], v[40:43]
	v_mfma_f32_16x16x32_bf16 v[40:43], v[166:169], v[198:201], v[40:43]
	v_mfma_f32_16x16x32_bf16 v[56:59], v[166:169], v[190:193], v[56:59]
	v_mfma_f32_16x16x32_bf16 v[56:59], v[162:165], v[186:189], v[56:59]
	v_mfma_f32_16x16x32_bf16 v[52:55], v[170:173], v[186:189], v[52:55]
	v_mfma_f32_16x16x32_bf16 v[52:55], v[174:177], v[190:193], v[52:55]
	v_mfma_f32_16x16x32_bf16 v[36:39], v[174:177], v[198:201], v[36:39]
	v_mfma_f32_16x16x32_bf16 v[36:39], v[170:173], v[194:197], v[36:39]
	v_mfma_f32_16x16x32_bf16 v[20:23], v[170:173], v[202:205], v[20:23]
	v_mfma_f32_16x16x32_bf16 v[20:23], v[174:177], v[206:209], v[20:23]
	v_mfma_f32_16x16x32_bf16 v[4:7], v[174:177], v[214:217], v[4:7]
	v_mfma_f32_16x16x32_bf16 v[4:7], v[170:173], v[210:213], v[4:7]
	v_mfma_f32_16x16x32_bf16 v[0:3], v[178:181], v[210:213], v[0:3]
	v_mfma_f32_16x16x32_bf16 v[0:3], v[182:185], v[214:217], v[0:3]
	v_mfma_f32_16x16x32_bf16 v[16:19], v[182:185], v[206:209], v[16:19]
	v_mfma_f32_16x16x32_bf16 v[16:19], v[178:181], v[202:205], v[16:19]
	v_mfma_f32_16x16x32_bf16 v[32:35], v[178:181], v[194:197], v[32:35]
	v_mfma_f32_16x16x32_bf16 v[32:35], v[182:185], v[198:201], v[32:35]
	v_mfma_f32_16x16x32_bf16 v[48:51], v[182:185], v[190:193], v[48:51]
	v_mfma_f32_16x16x32_bf16 v[48:51], v[178:181], v[186:189], v[48:51]
	s_barrier
	s_add_i32 s59, 0, 0x18000
	s_add_i32 s60, 0, 0x1c000
	v_add_u32_e32 v166, s59, v152
	v_add_u32_e32 v182, s60, v152
	ds_read_b128 v[154:157], v166
	ds_read_b128 v[158:161], v166 offset:1024
	ds_read_b128 v[162:165], v166 offset:2048
	ds_read_b128 v[166:169], v166 offset:3072
	ds_read_b128 v[170:173], v182
	ds_read_b128 v[174:177], v182 offset:1024
	ds_read_b128 v[178:181], v182 offset:2048
	ds_read_b128 v[182:185], v182 offset:3072
	s_add_u32 s34, s34, 0x100000
	s_addc_u32 s35, s35, 0
	s_mov_b32 m0, s46
	v_lshl_add_u64 v[186:187], s[34:35], 0, v[128:129]
	global_load_lds_dwordx4 v[186:187], off
	v_lshl_add_u64 v[186:187], s[34:35], 0, v[132:133]
	s_mov_b32 m0, s47
	s_nop 0
	global_load_lds_dwordx4 v[186:187], off
	ds_read_b128 v[186:189], v153 offset:32768
	ds_read_b128 v[190:193], v153 offset:33792
	ds_read_b128 v[194:197], v153 offset:34816
	ds_read_b128 v[198:201], v153 offset:35840
	ds_read_b128 v[202:205], v153 offset:36864
	ds_read_b128 v[206:209], v153 offset:37888
	ds_read_b128 v[210:213], v153 offset:38912
	ds_read_b128 v[214:217], v153 offset:39936
	s_waitcnt vmcnt(8)
	s_waitcnt lgkmcnt(0)
	s_barrier
	s_waitcnt lgkmcnt(0)
	v_mfma_f32_16x16x32_bf16 v[124:127], v[154:157], v[186:189], v[124:127]
	v_mfma_f32_16x16x32_bf16 v[124:127], v[158:161], v[190:193], v[124:127]
	v_mfma_f32_16x16x32_bf16 v[108:111], v[158:161], v[198:201], v[108:111]
	v_mfma_f32_16x16x32_bf16 v[108:111], v[154:157], v[194:197], v[108:111]
	v_mfma_f32_16x16x32_bf16 v[92:95], v[154:157], v[202:205], v[92:95]
	v_mfma_f32_16x16x32_bf16 v[92:95], v[158:161], v[206:209], v[92:95]
	v_mfma_f32_16x16x32_bf16 v[76:79], v[158:161], v[214:217], v[76:79]
	v_mfma_f32_16x16x32_bf16 v[76:79], v[154:157], v[210:213], v[76:79]
	v_mfma_f32_16x16x32_bf16 v[72:75], v[162:165], v[210:213], v[72:75]
	v_mfma_f32_16x16x32_bf16 v[72:75], v[166:169], v[214:217], v[72:75]
	v_mfma_f32_16x16x32_bf16 v[88:91], v[166:169], v[206:209], v[88:91]
	v_mfma_f32_16x16x32_bf16 v[88:91], v[162:165], v[202:205], v[88:91]
	v_mfma_f32_16x16x32_bf16 v[104:107], v[162:165], v[194:197], v[104:107]
	v_mfma_f32_16x16x32_bf16 v[104:107], v[166:169], v[198:201], v[104:107]
	v_mfma_f32_16x16x32_bf16 v[120:123], v[166:169], v[190:193], v[120:123]
	v_mfma_f32_16x16x32_bf16 v[120:123], v[162:165], v[186:189], v[120:123]
	v_mfma_f32_16x16x32_bf16 v[116:119], v[170:173], v[186:189], v[116:119]
	v_mfma_f32_16x16x32_bf16 v[116:119], v[174:177], v[190:193], v[116:119]
	v_mfma_f32_16x16x32_bf16 v[100:103], v[174:177], v[198:201], v[100:103]
	v_mfma_f32_16x16x32_bf16 v[100:103], v[170:173], v[194:197], v[100:103]
	v_mfma_f32_16x16x32_bf16 v[84:87], v[170:173], v[202:205], v[84:87]
	v_mfma_f32_16x16x32_bf16 v[84:87], v[174:177], v[206:209], v[84:87]
	v_mfma_f32_16x16x32_bf16 v[68:71], v[174:177], v[214:217], v[68:71]
	v_mfma_f32_16x16x32_bf16 v[68:71], v[170:173], v[210:213], v[68:71]
	v_mfma_f32_16x16x32_bf16 v[64:67], v[178:181], v[210:213], v[64:67]
	v_mfma_f32_16x16x32_bf16 v[64:67], v[182:185], v[214:217], v[64:67]
	v_mfma_f32_16x16x32_bf16 v[80:83], v[182:185], v[206:209], v[80:83]
	v_mfma_f32_16x16x32_bf16 v[80:83], v[178:181], v[202:205], v[80:83]
	v_mfma_f32_16x16x32_bf16 v[96:99], v[178:181], v[194:197], v[96:99]
	v_mfma_f32_16x16x32_bf16 v[96:99], v[182:185], v[198:201], v[96:99]
	v_mfma_f32_16x16x32_bf16 v[112:115], v[182:185], v[190:193], v[112:115]
	v_mfma_f32_16x16x32_bf16 v[112:115], v[178:181], v[186:189], v[112:115]
	s_barrier
	s_add_i32 s34, s59, s43
	v_lshl_add_u64 v[186:187], v[218:219], 0, s[14:15]
	s_mov_b32 m0, s34
	s_nop 0
	global_load_lds_dwordx4 v[186:187], off
	s_add_i32 m0, s34, 0x2000
	s_add_u32 s30, s30, 0x100080
	v_lshl_add_u64 v[186:187], v[220:221], 0, s[14:15]
	s_addc_u32 s31, s31, 0
	s_add_i32 s34, s60, s43
	global_load_lds_dwordx4 v[186:187], off
	v_lshl_add_u64 v[186:187], s[30:31], 0, v[130:131]
	s_mov_b32 m0, s34
	s_nop 0
	global_load_lds_dwordx4 v[186:187], off
	v_lshl_add_u64 v[186:187], s[30:31], 0, v[134:135]
	s_add_i32 m0, s34, 0x2000
	s_nop 0
	global_load_lds_dwordx4 v[186:187], off
	v_lshl_add_u64 v[186:187], v[222:223], 0, s[16:17]
	s_mov_b32 m0, s49
	s_nop 0
	global_load_lds_dwordx4 v[186:187], off
	v_lshl_add_u64 v[186:187], v[224:225], 0, s[16:17]
	s_mov_b32 m0, s50
	s_nop 0
	global_load_lds_dwordx4 v[186:187], off
	ds_read_b128 v[186:189], v153 offset:49152
	ds_read_b128 v[190:193], v153 offset:50176
	ds_read_b128 v[194:197], v153 offset:51200
	ds_read_b128 v[198:201], v153 offset:52224
	ds_read_b128 v[202:205], v153 offset:53248
	ds_read_b128 v[206:209], v153 offset:54272
	ds_read_b128 v[210:213], v153 offset:55296
	ds_read_b128 v[214:217], v153 offset:56320
	s_waitcnt vmcnt(8)
	s_waitcnt lgkmcnt(0)
	s_barrier
	s_waitcnt lgkmcnt(0)
	v_mfma_f32_16x16x32_bf16 v[60:63], v[154:157], v[186:189], v[60:63]
	v_mfma_f32_16x16x32_bf16 v[60:63], v[158:161], v[190:193], v[60:63]
	v_mfma_f32_16x16x32_bf16 v[44:47], v[158:161], v[198:201], v[44:47]
	v_mfma_f32_16x16x32_bf16 v[44:47], v[154:157], v[194:197], v[44:47]
	v_mfma_f32_16x16x32_bf16 v[28:31], v[154:157], v[202:205], v[28:31]
	v_mfma_f32_16x16x32_bf16 v[28:31], v[158:161], v[206:209], v[28:31]
	v_mfma_f32_16x16x32_bf16 v[12:15], v[158:161], v[214:217], v[12:15]
	v_mfma_f32_16x16x32_bf16 v[12:15], v[154:157], v[210:213], v[12:15]
	v_mfma_f32_16x16x32_bf16 v[8:11], v[162:165], v[210:213], v[8:11]
	v_mfma_f32_16x16x32_bf16 v[8:11], v[166:169], v[214:217], v[8:11]
	v_mfma_f32_16x16x32_bf16 v[24:27], v[166:169], v[206:209], v[24:27]
	v_mfma_f32_16x16x32_bf16 v[24:27], v[162:165], v[202:205], v[24:27]
	v_mfma_f32_16x16x32_bf16 v[40:43], v[162:165], v[194:197], v[40:43]
	v_mfma_f32_16x16x32_bf16 v[40:43], v[166:169], v[198:201], v[40:43]
	v_mfma_f32_16x16x32_bf16 v[56:59], v[166:169], v[190:193], v[56:59]
	v_mfma_f32_16x16x32_bf16 v[56:59], v[162:165], v[186:189], v[56:59]
	v_mfma_f32_16x16x32_bf16 v[52:55], v[170:173], v[186:189], v[52:55]
	v_mfma_f32_16x16x32_bf16 v[52:55], v[174:177], v[190:193], v[52:55]
	v_mfma_f32_16x16x32_bf16 v[36:39], v[174:177], v[198:201], v[36:39]
	v_mfma_f32_16x16x32_bf16 v[36:39], v[170:173], v[194:197], v[36:39]
	v_mfma_f32_16x16x32_bf16 v[20:23], v[170:173], v[202:205], v[20:23]
	v_mfma_f32_16x16x32_bf16 v[20:23], v[174:177], v[206:209], v[20:23]
	v_mfma_f32_16x16x32_bf16 v[4:7], v[174:177], v[214:217], v[4:7]
	v_mfma_f32_16x16x32_bf16 v[4:7], v[170:173], v[210:213], v[4:7]
	v_mfma_f32_16x16x32_bf16 v[0:3], v[178:181], v[210:213], v[0:3]
	v_mfma_f32_16x16x32_bf16 v[0:3], v[182:185], v[214:217], v[0:3]
	v_mfma_f32_16x16x32_bf16 v[16:19], v[182:185], v[206:209], v[16:19]
	v_mfma_f32_16x16x32_bf16 v[16:19], v[178:181], v[202:205], v[16:19]
	v_mfma_f32_16x16x32_bf16 v[32:35], v[178:181], v[194:197], v[32:35]
	v_mfma_f32_16x16x32_bf16 v[32:35], v[182:185], v[198:201], v[32:35]
	v_mfma_f32_16x16x32_bf16 v[48:51], v[182:185], v[190:193], v[48:51]
	v_mfma_f32_16x16x32_bf16 v[48:51], v[178:181], v[186:189], v[48:51]
	s_barrier
	s_add_i32 s58, s58, 2
	s_add_u32 s56, s56, 0x100
	s_addc_u32 s57, s57, 0
	s_add_u32 s28, s28, 0x1000
	s_addc_u32 s29, s29, 0
	v_lshl_add_u64 v[146:147], v[146:147], 0, s[18:19]
	s_cmp_gt_u32 s58, 61
	v_lshl_add_u64 v[144:145], v[144:145], 0, s[18:19]
	s_cbranch_scc0 .LBB0_1340
	s_andn2_b64 vcc, exec, s[4:5]
	s_cbranch_vccnz .LBB0_1332
	v_mov_b32_e32 v0, 0
	s_mov_b32 s7, s20
	s_mov_b32 s6, s22
	s_mov_b64 s[8:9], s[26:27]
	s_mov_b64 s[10:11], s[24:25]
	s_mov_b32 s48, s53
	v_mov_b32_e32 v1, v0
	v_mov_b32_e32 v2, v0
	v_mov_b32_e32 v3, v0
	v_mov_b32_e32 v4, v0
	v_mov_b32_e32 v5, v0
	v_mov_b32_e32 v6, v0
	v_mov_b32_e32 v7, v0
	v_mov_b32_e32 v16, v0
	v_mov_b32_e32 v17, v0
	v_mov_b32_e32 v18, v0
	v_mov_b32_e32 v19, v0
	v_mov_b32_e32 v20, v0
	v_mov_b32_e32 v21, v0
	v_mov_b32_e32 v22, v0
	v_mov_b32_e32 v23, v0
	v_mov_b32_e32 v32, v0
	v_mov_b32_e32 v33, v0
	v_mov_b32_e32 v34, v0
	v_mov_b32_e32 v35, v0
	v_mov_b32_e32 v36, v0
	v_mov_b32_e32 v37, v0
	v_mov_b32_e32 v38, v0
	v_mov_b32_e32 v39, v0
	v_mov_b32_e32 v48, v0
	v_mov_b32_e32 v49, v0
	v_mov_b32_e32 v50, v0
	v_mov_b32_e32 v51, v0
	v_mov_b32_e32 v52, v0
	v_mov_b32_e32 v53, v0
	v_mov_b32_e32 v54, v0
	v_mov_b32_e32 v55, v0
	v_mov_b32_e32 v8, v0
	v_mov_b32_e32 v9, v0
	v_mov_b32_e32 v10, v0
	v_mov_b32_e32 v11, v0
	v_mov_b32_e32 v12, v0
	v_mov_b32_e32 v13, v0
	v_mov_b32_e32 v14, v0
	v_mov_b32_e32 v15, v0
	v_mov_b32_e32 v24, v0
	v_mov_b32_e32 v25, v0
	v_mov_b32_e32 v26, v0
	v_mov_b32_e32 v27, v0
	v_mov_b32_e32 v28, v0
	v_mov_b32_e32 v29, v0
	v_mov_b32_e32 v30, v0
	v_mov_b32_e32 v31, v0
	v_mov_b32_e32 v40, v0
	v_mov_b32_e32 v41, v0
	v_mov_b32_e32 v42, v0
	v_mov_b32_e32 v43, v0
	v_mov_b32_e32 v44, v0
	v_mov_b32_e32 v45, v0
	v_mov_b32_e32 v46, v0
	v_mov_b32_e32 v47, v0
	v_mov_b32_e32 v56, v0
	v_mov_b32_e32 v57, v0
	v_mov_b32_e32 v58, v0
	v_mov_b32_e32 v59, v0
	v_mov_b32_e32 v60, v0
	v_mov_b32_e32 v61, v0
	v_mov_b32_e32 v62, v0
	v_mov_b32_e32 v63, v0
	v_mov_b32_e32 v64, v0
	v_mov_b32_e32 v65, v0
	v_mov_b32_e32 v66, v0
	v_mov_b32_e32 v67, v0
	v_mov_b32_e32 v68, v0
	v_mov_b32_e32 v69, v0
	v_mov_b32_e32 v70, v0
	v_mov_b32_e32 v71, v0
	v_mov_b32_e32 v80, v0
	v_mov_b32_e32 v81, v0
	v_mov_b32_e32 v82, v0
	v_mov_b32_e32 v83, v0
	v_mov_b32_e32 v84, v0
	v_mov_b32_e32 v85, v0
	v_mov_b32_e32 v86, v0
	v_mov_b32_e32 v87, v0
	v_mov_b32_e32 v96, v0
	v_mov_b32_e32 v97, v0
	v_mov_b32_e32 v98, v0
	v_mov_b32_e32 v99, v0
	v_mov_b32_e32 v100, v0
	v_mov_b32_e32 v101, v0
	v_mov_b32_e32 v102, v0
	v_mov_b32_e32 v103, v0
	v_mov_b32_e32 v112, v0
	v_mov_b32_e32 v113, v0
	v_mov_b32_e32 v114, v0
	v_mov_b32_e32 v115, v0
	v_mov_b32_e32 v116, v0
	v_mov_b32_e32 v117, v0
	v_mov_b32_e32 v118, v0
	v_mov_b32_e32 v119, v0
	v_mov_b32_e32 v72, v0
	v_mov_b32_e32 v73, v0
	v_mov_b32_e32 v74, v0
	v_mov_b32_e32 v75, v0
	v_mov_b32_e32 v76, v0
	v_mov_b32_e32 v77, v0
	v_mov_b32_e32 v78, v0
	v_mov_b32_e32 v79, v0
	v_mov_b32_e32 v88, v0
	v_mov_b32_e32 v89, v0
	v_mov_b32_e32 v90, v0
	v_mov_b32_e32 v91, v0
	v_mov_b32_e32 v92, v0
	v_mov_b32_e32 v93, v0
	v_mov_b32_e32 v94, v0
	v_mov_b32_e32 v95, v0
	v_mov_b32_e32 v104, v0
	v_mov_b32_e32 v105, v0
	v_mov_b32_e32 v106, v0
	v_mov_b32_e32 v107, v0
	v_mov_b32_e32 v108, v0
	v_mov_b32_e32 v109, v0
	v_mov_b32_e32 v110, v0
	v_mov_b32_e32 v111, v0
	v_mov_b32_e32 v120, v0
	v_mov_b32_e32 v121, v0
	v_mov_b32_e32 v122, v0
	v_mov_b32_e32 v123, v0
	v_mov_b32_e32 v124, v0
	v_mov_b32_e32 v125, v0
	v_mov_b32_e32 v126, v0
	v_mov_b32_e32 v127, v0
	s_branch .LBB0_1332

.LBB0_1435:
	ds_read_b128 v[128:131], v180
	ds_read_b128 v[132:135], v180 offset:1024
	ds_read_b128 v[136:139], v180 offset:2048
	ds_read_b128 v[140:143], v180 offset:3072
	ds_read_b128 v[144:147], v181
	ds_read_b128 v[148:151], v181 offset:1024
	ds_read_b128 v[170:173], v181 offset:2048
	ds_read_b128 v[174:177], v181 offset:3072
	s_add_u32 s26, s24, 0xfffc0080
	s_addc_u32 s27, s25, -1
	s_cmp_eq_u32 s35, 12
	s_cselect_b32 s29, s1, s27
	s_cselect_b32 s28, s19, s26
	s_cselect_b32 s27, s17, s34
	s_cselect_b32 s26, s30, s31
	v_lshl_add_u64 v[184:185], s[24:25], 0, v[162:163]
	s_add_i32 m0, s40, 0xc000
	s_nop 0
	global_load_lds_dwordx4 v[184:185], off
	v_lshl_add_u64 v[184:185], s[24:25], 0, v[164:165]
	s_add_i32 m0, s40, 0xe000
	s_nop 0
	global_load_lds_dwordx4 v[184:185], off
	ds_read_b128 v[184:187], v182
	ds_read_b128 v[188:191], v182 offset:1024
	ds_read_b128 v[192:195], v182 offset:2048
	ds_read_b128 v[196:199], v182 offset:3072
	ds_read_b128 v[200:203], v182 offset:4096
	ds_read_b128 v[204:207], v182 offset:5120
	ds_read_b128 v[208:211], v182 offset:6144
	ds_read_b128 v[212:215], v182 offset:7168
	s_waitcnt vmcnt(8)
	s_waitcnt lgkmcnt(0)
	s_barrier
	s_waitcnt lgkmcnt(0)
	v_mfma_f32_16x16x32_bf16 v[124:127], v[128:131], v[184:187], v[124:127]
	v_mfma_f32_16x16x32_bf16 v[124:127], v[132:135], v[188:191], v[124:127]
	v_mfma_f32_16x16x32_bf16 v[108:111], v[132:135], v[196:199], v[108:111]
	v_mfma_f32_16x16x32_bf16 v[108:111], v[128:131], v[192:195], v[108:111]
	v_mfma_f32_16x16x32_bf16 v[92:95], v[128:131], v[200:203], v[92:95]
	v_mfma_f32_16x16x32_bf16 v[92:95], v[132:135], v[204:207], v[92:95]
	v_mfma_f32_16x16x32_bf16 v[76:79], v[132:135], v[212:215], v[76:79]
	v_mfma_f32_16x16x32_bf16 v[76:79], v[128:131], v[208:211], v[76:79]
	v_mfma_f32_16x16x32_bf16 v[72:75], v[136:139], v[208:211], v[72:75]
	v_mfma_f32_16x16x32_bf16 v[72:75], v[140:143], v[212:215], v[72:75]
	v_mfma_f32_16x16x32_bf16 v[88:91], v[140:143], v[204:207], v[88:91]
	v_mfma_f32_16x16x32_bf16 v[88:91], v[136:139], v[200:203], v[88:91]
	v_mfma_f32_16x16x32_bf16 v[104:107], v[136:139], v[192:195], v[104:107]
	v_mfma_f32_16x16x32_bf16 v[104:107], v[140:143], v[196:199], v[104:107]
	v_mfma_f32_16x16x32_bf16 v[120:123], v[140:143], v[188:191], v[120:123]
	v_mfma_f32_16x16x32_bf16 v[120:123], v[136:139], v[184:187], v[120:123]
	v_mfma_f32_16x16x32_bf16 v[116:119], v[144:147], v[184:187], v[116:119]
	v_mfma_f32_16x16x32_bf16 v[116:119], v[148:151], v[188:191], v[116:119]
	v_mfma_f32_16x16x32_bf16 v[100:103], v[148:151], v[196:199], v[100:103]
	v_mfma_f32_16x16x32_bf16 v[100:103], v[144:147], v[192:195], v[100:103]
	v_mfma_f32_16x16x32_bf16 v[84:87], v[144:147], v[200:203], v[84:87]
	v_mfma_f32_16x16x32_bf16 v[84:87], v[148:151], v[204:207], v[84:87]
	v_mfma_f32_16x16x32_bf16 v[68:71], v[148:151], v[212:215], v[68:71]
	v_mfma_f32_16x16x32_bf16 v[68:71], v[144:147], v[208:211], v[68:71]
	v_mfma_f32_16x16x32_bf16 v[64:67], v[170:173], v[208:211], v[64:67]
	v_mfma_f32_16x16x32_bf16 v[64:67], v[174:177], v[212:215], v[64:67]
	v_mfma_f32_16x16x32_bf16 v[80:83], v[174:177], v[204:207], v[80:83]
	v_mfma_f32_16x16x32_bf16 v[80:83], v[170:173], v[200:203], v[80:83]
	v_mfma_f32_16x16x32_bf16 v[96:99], v[170:173], v[192:195], v[96:99]
	v_mfma_f32_16x16x32_bf16 v[96:99], v[174:177], v[196:199], v[96:99]
	v_mfma_f32_16x16x32_bf16 v[112:115], v[174:177], v[188:191], v[112:115]
	v_mfma_f32_16x16x32_bf16 v[112:115], v[170:173], v[184:187], v[112:115]
	s_barrier
	s_add_i32 s54, s50, s39
	v_lshl_add_u64 v[216:217], s[26:27], 0, v[154:155]
	s_mov_b32 m0, s54
	v_lshl_add_u64 v[218:219], s[26:27], 0, v[158:159]
	global_load_lds_dwordx4 v[216:217], off
	s_add_i32 m0, s54, 0x2000
	s_add_u32 s54, s26, 0x100000
	s_addc_u32 s55, s27, 0
	s_add_i32 s56, s51, s39
	global_load_lds_dwordx4 v[218:219], off
	v_lshl_add_u64 v[184:185], s[54:55], 0, v[154:155]
	s_mov_b32 m0, s56
	v_lshl_add_u64 v[220:221], s[28:29], 0, v[152:153]
	global_load_lds_dwordx4 v[184:185], off
	v_lshl_add_u64 v[184:185], s[54:55], 0, v[158:159]
	s_add_i32 m0, s56, 0x2000
	v_lshl_add_u64 v[222:223], s[28:29], 0, v[156:157]
	global_load_lds_dwordx4 v[184:185], off
	s_mov_b32 m0, s40
	s_nop 0
	global_load_lds_dwordx4 v[220:221], off
	s_mov_b32 m0, s41
	s_nop 0
	global_load_lds_dwordx4 v[222:223], off
	ds_read_b128 v[184:187], v182 offset:16384
	ds_read_b128 v[188:191], v182 offset:17408
	ds_read_b128 v[192:195], v182 offset:18432
	ds_read_b128 v[196:199], v182 offset:19456
	ds_read_b128 v[200:203], v182 offset:20480
	ds_read_b128 v[204:207], v182 offset:21504
	ds_read_b128 v[208:211], v182 offset:22528
	ds_read_b128 v[212:215], v182 offset:23552
	s_waitcnt vmcnt(8)
	s_waitcnt lgkmcnt(0)
	s_barrier
	s_waitcnt lgkmcnt(0)
	v_mfma_f32_16x16x32_bf16 v[60:63], v[128:131], v[184:187], v[60:63]
	v_mfma_f32_16x16x32_bf16 v[60:63], v[132:135], v[188:191], v[60:63]
	v_mfma_f32_16x16x32_bf16 v[44:47], v[132:135], v[196:199], v[44:47]
	v_mfma_f32_16x16x32_bf16 v[44:47], v[128:131], v[192:195], v[44:47]
	v_mfma_f32_16x16x32_bf16 v[28:31], v[128:131], v[200:203], v[28:31]
	v_mfma_f32_16x16x32_bf16 v[28:31], v[132:135], v[204:207], v[28:31]
	v_mfma_f32_16x16x32_bf16 v[12:15], v[132:135], v[212:215], v[12:15]
	v_mfma_f32_16x16x32_bf16 v[12:15], v[128:131], v[208:211], v[12:15]
	v_mfma_f32_16x16x32_bf16 v[8:11], v[136:139], v[208:211], v[8:11]
	v_mfma_f32_16x16x32_bf16 v[8:11], v[140:143], v[212:215], v[8:11]
	v_mfma_f32_16x16x32_bf16 v[24:27], v[140:143], v[204:207], v[24:27]
	v_mfma_f32_16x16x32_bf16 v[24:27], v[136:139], v[200:203], v[24:27]
	v_mfma_f32_16x16x32_bf16 v[40:43], v[136:139], v[192:195], v[40:43]
	v_mfma_f32_16x16x32_bf16 v[40:43], v[140:143], v[196:199], v[40:43]
	v_mfma_f32_16x16x32_bf16 v[56:59], v[140:143], v[188:191], v[56:59]
	v_mfma_f32_16x16x32_bf16 v[56:59], v[136:139], v[184:187], v[56:59]
	v_mfma_f32_16x16x32_bf16 v[52:55], v[144:147], v[184:187], v[52:55]
	v_mfma_f32_16x16x32_bf16 v[52:55], v[148:151], v[188:191], v[52:55]
	v_mfma_f32_16x16x32_bf16 v[36:39], v[148:151], v[196:199], v[36:39]
	v_mfma_f32_16x16x32_bf16 v[36:39], v[144:147], v[192:195], v[36:39]
	v_mfma_f32_16x16x32_bf16 v[20:23], v[144:147], v[200:203], v[20:23]
	v_mfma_f32_16x16x32_bf16 v[20:23], v[148:151], v[204:207], v[20:23]
	v_mfma_f32_16x16x32_bf16 v[4:7], v[148:151], v[212:215], v[4:7]
	v_mfma_f32_16x16x32_bf16 v[4:7], v[144:147], v[208:211], v[4:7]
	v_mfma_f32_16x16x32_bf16 v[0:3], v[170:173], v[208:211], v[0:3]
	v_mfma_f32_16x16x32_bf16 v[0:3], v[174:177], v[212:215], v[0:3]
	v_mfma_f32_16x16x32_bf16 v[16:19], v[174:177], v[204:207], v[16:19]
	v_mfma_f32_16x16x32_bf16 v[16:19], v[170:173], v[200:203], v[16:19]
	v_mfma_f32_16x16x32_bf16 v[32:35], v[170:173], v[192:195], v[32:35]
	v_mfma_f32_16x16x32_bf16 v[32:35], v[174:177], v[196:199], v[32:35]
	v_mfma_f32_16x16x32_bf16 v[48:51], v[174:177], v[188:191], v[48:51]
	v_mfma_f32_16x16x32_bf16 v[48:51], v[170:173], v[184:187], v[48:51]
	s_barrier
	s_add_i32 s54, 0, 0x18000
	s_add_i32 s55, 0, 0x1c000
	v_add_u32_e32 v140, s54, v178
	v_add_u32_e32 v174, s55, v178
	ds_read_b128 v[128:131], v140
	ds_read_b128 v[132:135], v140 offset:1024
	ds_read_b128 v[136:139], v140 offset:2048
	ds_read_b128 v[140:143], v140 offset:3072
	ds_read_b128 v[144:147], v174
	ds_read_b128 v[148:151], v174 offset:1024
	ds_read_b128 v[170:173], v174 offset:2048
	ds_read_b128 v[174:177], v174 offset:3072
	s_add_u32 s28, s28, 0x40000
	s_addc_u32 s29, s29, 0
	s_mov_b32 m0, s42
	v_lshl_add_u64 v[184:185], s[28:29], 0, v[152:153]
	global_load_lds_dwordx4 v[184:185], off
	v_lshl_add_u64 v[184:185], s[28:29], 0, v[156:157]
	s_mov_b32 m0, s43
	s_nop 0
	global_load_lds_dwordx4 v[184:185], off
	ds_read_b128 v[184:187], v182 offset:32768
	ds_read_b128 v[188:191], v182 offset:33792
	ds_read_b128 v[192:195], v182 offset:34816
	ds_read_b128 v[196:199], v182 offset:35840
	ds_read_b128 v[200:203], v182 offset:36864
	ds_read_b128 v[204:207], v182 offset:37888
	ds_read_b128 v[208:211], v182 offset:38912
	ds_read_b128 v[212:215], v182 offset:39936
	s_waitcnt vmcnt(8)
	s_waitcnt lgkmcnt(0)
	s_barrier
	s_waitcnt lgkmcnt(0)
	v_mfma_f32_16x16x32_bf16 v[124:127], v[128:131], v[184:187], v[124:127]
	v_mfma_f32_16x16x32_bf16 v[124:127], v[132:135], v[188:191], v[124:127]
	v_mfma_f32_16x16x32_bf16 v[108:111], v[132:135], v[196:199], v[108:111]
	v_mfma_f32_16x16x32_bf16 v[108:111], v[128:131], v[192:195], v[108:111]
	v_mfma_f32_16x16x32_bf16 v[92:95], v[128:131], v[200:203], v[92:95]
	v_mfma_f32_16x16x32_bf16 v[92:95], v[132:135], v[204:207], v[92:95]
	v_mfma_f32_16x16x32_bf16 v[76:79], v[132:135], v[212:215], v[76:79]
	v_mfma_f32_16x16x32_bf16 v[76:79], v[128:131], v[208:211], v[76:79]
	v_mfma_f32_16x16x32_bf16 v[72:75], v[136:139], v[208:211], v[72:75]
	v_mfma_f32_16x16x32_bf16 v[72:75], v[140:143], v[212:215], v[72:75]
	v_mfma_f32_16x16x32_bf16 v[88:91], v[140:143], v[204:207], v[88:91]
	v_mfma_f32_16x16x32_bf16 v[88:91], v[136:139], v[200:203], v[88:91]
	v_mfma_f32_16x16x32_bf16 v[104:107], v[136:139], v[192:195], v[104:107]
	v_mfma_f32_16x16x32_bf16 v[104:107], v[140:143], v[196:199], v[104:107]
	v_mfma_f32_16x16x32_bf16 v[120:123], v[140:143], v[188:191], v[120:123]
	v_mfma_f32_16x16x32_bf16 v[120:123], v[136:139], v[184:187], v[120:123]
	v_mfma_f32_16x16x32_bf16 v[116:119], v[144:147], v[184:187], v[116:119]
	v_mfma_f32_16x16x32_bf16 v[116:119], v[148:151], v[188:191], v[116:119]
	v_mfma_f32_16x16x32_bf16 v[100:103], v[148:151], v[196:199], v[100:103]
	v_mfma_f32_16x16x32_bf16 v[100:103], v[144:147], v[192:195], v[100:103]
	v_mfma_f32_16x16x32_bf16 v[84:87], v[144:147], v[200:203], v[84:87]
	v_mfma_f32_16x16x32_bf16 v[84:87], v[148:151], v[204:207], v[84:87]
	v_mfma_f32_16x16x32_bf16 v[68:71], v[148:151], v[212:215], v[68:71]
	v_mfma_f32_16x16x32_bf16 v[68:71], v[144:147], v[208:211], v[68:71]
	v_mfma_f32_16x16x32_bf16 v[64:67], v[170:173], v[208:211], v[64:67]
	v_mfma_f32_16x16x32_bf16 v[64:67], v[174:177], v[212:215], v[64:67]
	v_mfma_f32_16x16x32_bf16 v[80:83], v[174:177], v[204:207], v[80:83]
	v_mfma_f32_16x16x32_bf16 v[80:83], v[170:173], v[200:203], v[80:83]
	v_mfma_f32_16x16x32_bf16 v[96:99], v[170:173], v[192:195], v[96:99]
	v_mfma_f32_16x16x32_bf16 v[96:99], v[174:177], v[196:199], v[96:99]
	v_mfma_f32_16x16x32_bf16 v[112:115], v[174:177], v[188:191], v[112:115]
	v_mfma_f32_16x16x32_bf16 v[112:115], v[170:173], v[184:187], v[112:115]
	s_barrier
	s_add_i32 s28, s54, s39
	v_lshl_add_u64 v[184:185], v[216:217], 0, s[14:15]
	s_mov_b32 m0, s28
	s_nop 0
	global_load_lds_dwordx4 v[184:185], off
	s_add_i32 m0, s28, 0x2000
	s_add_u32 s26, s26, 0x100080
	v_lshl_add_u64 v[184:185], v[218:219], 0, s[14:15]
	s_addc_u32 s27, s27, 0
	s_add_i32 s28, s55, s39
	global_load_lds_dwordx4 v[184:185], off
	v_lshl_add_u64 v[184:185], s[26:27], 0, v[154:155]
	s_mov_b32 m0, s28
	s_nop 0
	global_load_lds_dwordx4 v[184:185], off
	v_lshl_add_u64 v[184:185], s[26:27], 0, v[158:159]
	s_add_i32 m0, s28, 0x2000
	s_nop 0
	global_load_lds_dwordx4 v[184:185], off
	v_lshl_add_u64 v[184:185], v[220:221], 0, s[14:15]
	s_mov_b32 m0, s45
	s_nop 0
	global_load_lds_dwordx4 v[184:185], off
	v_lshl_add_u64 v[184:185], v[222:223], 0, s[14:15]
	s_mov_b32 m0, s46
	s_nop 0
	global_load_lds_dwordx4 v[184:185], off
	ds_read_b128 v[184:187], v182 offset:49152
	ds_read_b128 v[188:191], v182 offset:50176
	ds_read_b128 v[192:195], v182 offset:51200
	ds_read_b128 v[196:199], v182 offset:52224
	ds_read_b128 v[200:203], v182 offset:53248
	ds_read_b128 v[204:207], v182 offset:54272
	ds_read_b128 v[208:211], v182 offset:55296
	ds_read_b128 v[212:215], v182 offset:56320
	s_waitcnt vmcnt(8)
	s_waitcnt lgkmcnt(0)
	s_barrier
	s_waitcnt lgkmcnt(0)
	v_mfma_f32_16x16x32_bf16 v[60:63], v[128:131], v[184:187], v[60:63]
	v_mfma_f32_16x16x32_bf16 v[60:63], v[132:135], v[188:191], v[60:63]
	v_mfma_f32_16x16x32_bf16 v[44:47], v[132:135], v[196:199], v[44:47]
	v_mfma_f32_16x16x32_bf16 v[44:47], v[128:131], v[192:195], v[44:47]
	v_mfma_f32_16x16x32_bf16 v[28:31], v[128:131], v[200:203], v[28:31]
	v_mfma_f32_16x16x32_bf16 v[28:31], v[132:135], v[204:207], v[28:31]
	v_mfma_f32_16x16x32_bf16 v[12:15], v[132:135], v[212:215], v[12:15]
	v_mfma_f32_16x16x32_bf16 v[12:15], v[128:131], v[208:211], v[12:15]
	v_mfma_f32_16x16x32_bf16 v[8:11], v[136:139], v[208:211], v[8:11]
	v_mfma_f32_16x16x32_bf16 v[8:11], v[140:143], v[212:215], v[8:11]
	v_mfma_f32_16x16x32_bf16 v[24:27], v[140:143], v[204:207], v[24:27]
	v_mfma_f32_16x16x32_bf16 v[24:27], v[136:139], v[200:203], v[24:27]
	v_mfma_f32_16x16x32_bf16 v[40:43], v[136:139], v[192:195], v[40:43]
	v_mfma_f32_16x16x32_bf16 v[40:43], v[140:143], v[196:199], v[40:43]
	v_mfma_f32_16x16x32_bf16 v[56:59], v[140:143], v[188:191], v[56:59]
	v_mfma_f32_16x16x32_bf16 v[56:59], v[136:139], v[184:187], v[56:59]
	v_mfma_f32_16x16x32_bf16 v[52:55], v[144:147], v[184:187], v[52:55]
	v_mfma_f32_16x16x32_bf16 v[52:55], v[148:151], v[188:191], v[52:55]
	v_mfma_f32_16x16x32_bf16 v[36:39], v[148:151], v[196:199], v[36:39]
	v_mfma_f32_16x16x32_bf16 v[36:39], v[144:147], v[192:195], v[36:39]
	v_mfma_f32_16x16x32_bf16 v[20:23], v[144:147], v[200:203], v[20:23]
	v_mfma_f32_16x16x32_bf16 v[20:23], v[148:151], v[204:207], v[20:23]
	v_mfma_f32_16x16x32_bf16 v[4:7], v[148:151], v[212:215], v[4:7]
	v_mfma_f32_16x16x32_bf16 v[4:7], v[144:147], v[208:211], v[4:7]
	v_mfma_f32_16x16x32_bf16 v[0:3], v[170:173], v[208:211], v[0:3]
	v_mfma_f32_16x16x32_bf16 v[0:3], v[174:177], v[212:215], v[0:3]
	v_mfma_f32_16x16x32_bf16 v[16:19], v[174:177], v[204:207], v[16:19]
	v_mfma_f32_16x16x32_bf16 v[16:19], v[170:173], v[200:203], v[16:19]
	v_mfma_f32_16x16x32_bf16 v[32:35], v[170:173], v[192:195], v[32:35]
	v_mfma_f32_16x16x32_bf16 v[32:35], v[174:177], v[196:199], v[32:35]
	v_mfma_f32_16x16x32_bf16 v[48:51], v[174:177], v[188:191], v[48:51]
	v_mfma_f32_16x16x32_bf16 v[48:51], v[170:173], v[184:187], v[48:51]
	s_barrier
	s_add_i32 s35, s35, 2
	s_add_u32 s24, s24, 0x100
	s_addc_u32 s25, s25, 0
	s_add_u32 s31, s31, 0x100
	s_addc_u32 s34, s34, 0
	s_cmp_gt_u32 s35, 13
	s_cbranch_scc0 .LBB0_1435
	s_and_b64 vcc, exec, s[8:9]
	s_cbranch_vccz .LBB0_1438
	s_barrier

.LBB0_1543:
	ds_read_b128 v[128:131], v167
	ds_read_b128 v[154:157], v167 offset:1024
	ds_read_b128 v[172:175], v167 offset:2048
	ds_read_b128 v[176:179], v167 offset:3072
	ds_read_b128 v[180:183], v168
	ds_read_b128 v[184:187], v168 offset:1024
	ds_read_b128 v[188:191], v168 offset:2048
	ds_read_b128 v[192:195], v168 offset:3072
	s_add_u32 s22, s20, 0x1000
	s_addc_u32 s23, s21, 0
	s_cmp_eq_u32 s54, 60
	s_cselect_b32 s27, s13, s23
	s_cselect_b32 s26, s50, s22
	s_cselect_b32 s25, s11, s53
	s_cselect_b32 s24, s51, s52
	v_lshl_add_u64 v[160:161], s[20:21], 0, v[144:145]
	s_add_i32 m0, s19, 0xc000
	s_nop 0
	global_load_lds_dwordx4 v[160:161], off
	v_lshl_add_u64 v[160:161], s[20:21], 0, v[146:147]
	s_add_i32 m0, s19, 0xe000
	s_nop 0
	global_load_lds_dwordx4 v[160:161], off
	ds_read_b128 v[196:199], v169
	ds_read_b128 v[200:203], v169 offset:1024
	ds_read_b128 v[204:207], v169 offset:2048
	ds_read_b128 v[208:211], v169 offset:3072
	ds_read_b128 v[212:215], v169 offset:4096
	ds_read_b128 v[216:219], v169 offset:5120
	ds_read_b128 v[220:223], v169 offset:6144
	ds_read_b128 v[224:227], v169 offset:7168
	s_waitcnt vmcnt(8)
	s_waitcnt lgkmcnt(0)
	s_barrier
	s_waitcnt lgkmcnt(0)
	v_mfma_f32_16x16x32_bf16 v[124:127], v[128:131], v[196:199], v[124:127]
	v_mfma_f32_16x16x32_bf16 v[124:127], v[154:157], v[200:203], v[124:127]
	v_mfma_f32_16x16x32_bf16 v[108:111], v[154:157], v[208:211], v[108:111]
	v_mfma_f32_16x16x32_bf16 v[108:111], v[128:131], v[204:207], v[108:111]
	v_mfma_f32_16x16x32_bf16 v[92:95], v[128:131], v[212:215], v[92:95]
	v_mfma_f32_16x16x32_bf16 v[92:95], v[154:157], v[216:219], v[92:95]
	v_mfma_f32_16x16x32_bf16 v[76:79], v[154:157], v[224:227], v[76:79]
	v_mfma_f32_16x16x32_bf16 v[76:79], v[128:131], v[220:223], v[76:79]
	v_mfma_f32_16x16x32_bf16 v[72:75], v[172:175], v[220:223], v[72:75]
	v_mfma_f32_16x16x32_bf16 v[72:75], v[176:179], v[224:227], v[72:75]
	v_mfma_f32_16x16x32_bf16 v[88:91], v[176:179], v[216:219], v[88:91]
	v_mfma_f32_16x16x32_bf16 v[88:91], v[172:175], v[212:215], v[88:91]
	v_mfma_f32_16x16x32_bf16 v[104:107], v[172:175], v[204:207], v[104:107]
	v_mfma_f32_16x16x32_bf16 v[104:107], v[176:179], v[208:211], v[104:107]
	v_mfma_f32_16x16x32_bf16 v[120:123], v[176:179], v[200:203], v[120:123]
	v_mfma_f32_16x16x32_bf16 v[120:123], v[172:175], v[196:199], v[120:123]
	v_mfma_f32_16x16x32_bf16 v[116:119], v[180:183], v[196:199], v[116:119]
	v_mfma_f32_16x16x32_bf16 v[116:119], v[184:187], v[200:203], v[116:119]
	v_mfma_f32_16x16x32_bf16 v[100:103], v[184:187], v[208:211], v[100:103]
	v_mfma_f32_16x16x32_bf16 v[100:103], v[180:183], v[204:207], v[100:103]
	v_mfma_f32_16x16x32_bf16 v[84:87], v[180:183], v[212:215], v[84:87]
	v_mfma_f32_16x16x32_bf16 v[84:87], v[184:187], v[216:219], v[84:87]
	v_mfma_f32_16x16x32_bf16 v[68:71], v[184:187], v[224:227], v[68:71]
	v_mfma_f32_16x16x32_bf16 v[68:71], v[180:183], v[220:223], v[68:71]
	v_mfma_f32_16x16x32_bf16 v[64:67], v[188:191], v[220:223], v[64:67]
	v_mfma_f32_16x16x32_bf16 v[64:67], v[192:195], v[224:227], v[64:67]
	v_mfma_f32_16x16x32_bf16 v[80:83], v[192:195], v[216:219], v[80:83]
	v_mfma_f32_16x16x32_bf16 v[80:83], v[188:191], v[212:215], v[80:83]
	v_mfma_f32_16x16x32_bf16 v[96:99], v[188:191], v[204:207], v[96:99]
	v_mfma_f32_16x16x32_bf16 v[96:99], v[192:195], v[208:211], v[96:99]
	v_mfma_f32_16x16x32_bf16 v[112:115], v[192:195], v[200:203], v[112:115]
	v_mfma_f32_16x16x32_bf16 v[112:115], v[188:191], v[196:199], v[112:115]
	s_barrier
	s_add_i32 s20, s45, s30
	v_lshl_add_u64 v[160:161], s[24:25], 0, v[134:135]
	s_mov_b32 m0, s20
	v_lshl_add_u64 v[164:165], s[24:25], 0, v[138:139]
	global_load_lds_dwordx4 v[160:161], off
	s_add_i32 m0, s20, 0x2000
	s_add_u32 s20, s24, 0x100000
	s_addc_u32 s21, s25, 0
	s_add_i32 s55, s46, s30
	global_load_lds_dwordx4 v[164:165], off
	v_lshl_add_u64 v[196:197], s[20:21], 0, v[134:135]
	s_mov_b32 m0, s55
	v_lshl_add_u64 v[228:229], s[26:27], 0, v[132:133]
	global_load_lds_dwordx4 v[196:197], off
	v_lshl_add_u64 v[196:197], s[20:21], 0, v[138:139]
	s_add_i32 m0, s55, 0x2000
	v_lshl_add_u64 v[230:231], s[26:27], 0, v[136:137]
	global_load_lds_dwordx4 v[196:197], off
	s_mov_b32 m0, s19
	s_nop 0
	global_load_lds_dwordx4 v[228:229], off
	s_mov_b32 m0, s36
	s_nop 0
	global_load_lds_dwordx4 v[230:231], off
	ds_read_b128 v[196:199], v169 offset:16384
	ds_read_b128 v[200:203], v169 offset:17408
	ds_read_b128 v[204:207], v169 offset:18432
	ds_read_b128 v[208:211], v169 offset:19456
	ds_read_b128 v[212:215], v169 offset:20480
	ds_read_b128 v[216:219], v169 offset:21504
	ds_read_b128 v[220:223], v169 offset:22528
	ds_read_b128 v[224:227], v169 offset:23552
	s_waitcnt vmcnt(8)
	s_waitcnt lgkmcnt(0)
	s_barrier
	s_waitcnt lgkmcnt(0)
	v_mfma_f32_16x16x32_bf16 v[60:63], v[128:131], v[196:199], v[60:63]
	v_mfma_f32_16x16x32_bf16 v[60:63], v[154:157], v[200:203], v[60:63]
	v_mfma_f32_16x16x32_bf16 v[44:47], v[154:157], v[208:211], v[44:47]
	v_mfma_f32_16x16x32_bf16 v[44:47], v[128:131], v[204:207], v[44:47]
	v_mfma_f32_16x16x32_bf16 v[28:31], v[128:131], v[212:215], v[28:31]
	v_mfma_f32_16x16x32_bf16 v[28:31], v[154:157], v[216:219], v[28:31]
	v_mfma_f32_16x16x32_bf16 v[12:15], v[154:157], v[224:227], v[12:15]
	v_mfma_f32_16x16x32_bf16 v[12:15], v[128:131], v[220:223], v[12:15]
	v_mfma_f32_16x16x32_bf16 v[8:11], v[172:175], v[220:223], v[8:11]
	v_mfma_f32_16x16x32_bf16 v[8:11], v[176:179], v[224:227], v[8:11]
	v_mfma_f32_16x16x32_bf16 v[24:27], v[176:179], v[216:219], v[24:27]
	v_mfma_f32_16x16x32_bf16 v[24:27], v[172:175], v[212:215], v[24:27]
	v_mfma_f32_16x16x32_bf16 v[40:43], v[172:175], v[204:207], v[40:43]
	v_mfma_f32_16x16x32_bf16 v[40:43], v[176:179], v[208:211], v[40:43]
	v_mfma_f32_16x16x32_bf16 v[56:59], v[176:179], v[200:203], v[56:59]
	v_mfma_f32_16x16x32_bf16 v[56:59], v[172:175], v[196:199], v[56:59]
	v_mfma_f32_16x16x32_bf16 v[52:55], v[180:183], v[196:199], v[52:55]
	v_mfma_f32_16x16x32_bf16 v[52:55], v[184:187], v[200:203], v[52:55]
	v_mfma_f32_16x16x32_bf16 v[36:39], v[184:187], v[208:211], v[36:39]
	v_mfma_f32_16x16x32_bf16 v[36:39], v[180:183], v[204:207], v[36:39]
	v_mfma_f32_16x16x32_bf16 v[20:23], v[180:183], v[212:215], v[20:23]
	v_mfma_f32_16x16x32_bf16 v[20:23], v[184:187], v[216:219], v[20:23]
	v_mfma_f32_16x16x32_bf16 v[4:7], v[184:187], v[224:227], v[4:7]
	v_mfma_f32_16x16x32_bf16 v[4:7], v[180:183], v[220:223], v[4:7]
	v_mfma_f32_16x16x32_bf16 v[0:3], v[188:191], v[220:223], v[0:3]
	v_mfma_f32_16x16x32_bf16 v[0:3], v[192:195], v[224:227], v[0:3]
	v_mfma_f32_16x16x32_bf16 v[16:19], v[192:195], v[216:219], v[16:19]
	v_mfma_f32_16x16x32_bf16 v[16:19], v[188:191], v[212:215], v[16:19]
	v_mfma_f32_16x16x32_bf16 v[32:35], v[188:191], v[204:207], v[32:35]
	v_mfma_f32_16x16x32_bf16 v[32:35], v[192:195], v[208:211], v[32:35]
	v_mfma_f32_16x16x32_bf16 v[48:51], v[192:195], v[200:203], v[48:51]
	v_mfma_f32_16x16x32_bf16 v[48:51], v[188:191], v[196:199], v[48:51]
	s_barrier
	s_add_i32 s55, 0, 0x18000
	v_add_u32_e32 v153, s55, v159
	s_add_i32 s56, 0, 0x1c000
	ds_read_b128 v[128:131], v153
	ds_read_b128 v[154:157], v153 offset:1024
	ds_read_b128 v[172:175], v153 offset:2048
	ds_read_b128 v[176:179], v153 offset:3072
	v_add_u32_e32 v153, s56, v159
	ds_read_b128 v[180:183], v153
	ds_read_b128 v[184:187], v153 offset:1024
	ds_read_b128 v[188:191], v153 offset:2048
	ds_read_b128 v[192:195], v153 offset:3072
	s_add_u32 s20, s26, 0x100000
	s_addc_u32 s21, s27, 0
	s_mov_b32 m0, s37
	v_lshl_add_u64 v[196:197], s[20:21], 0, v[132:133]
	global_load_lds_dwordx4 v[196:197], off
	v_lshl_add_u64 v[196:197], s[20:21], 0, v[136:137]
	s_mov_b32 m0, s38
	s_nop 0
	global_load_lds_dwordx4 v[196:197], off
	ds_read_b128 v[196:199], v169 offset:32768
	ds_read_b128 v[200:203], v169 offset:33792
	ds_read_b128 v[204:207], v169 offset:34816
	ds_read_b128 v[208:211], v169 offset:35840
	ds_read_b128 v[212:215], v169 offset:36864
	ds_read_b128 v[216:219], v169 offset:37888
	ds_read_b128 v[220:223], v169 offset:38912
	ds_read_b128 v[224:227], v169 offset:39936
	s_waitcnt vmcnt(8)
	s_waitcnt lgkmcnt(0)
	s_barrier
	s_waitcnt lgkmcnt(0)
	v_mfma_f32_16x16x32_bf16 v[124:127], v[128:131], v[196:199], v[124:127]
	v_mfma_f32_16x16x32_bf16 v[124:127], v[154:157], v[200:203], v[124:127]
	v_mfma_f32_16x16x32_bf16 v[108:111], v[154:157], v[208:211], v[108:111]
	v_mfma_f32_16x16x32_bf16 v[108:111], v[128:131], v[204:207], v[108:111]
	v_mfma_f32_16x16x32_bf16 v[92:95], v[128:131], v[212:215], v[92:95]
	v_mfma_f32_16x16x32_bf16 v[92:95], v[154:157], v[216:219], v[92:95]
	v_mfma_f32_16x16x32_bf16 v[76:79], v[154:157], v[224:227], v[76:79]
	v_mfma_f32_16x16x32_bf16 v[76:79], v[128:131], v[220:223], v[76:79]
	v_mfma_f32_16x16x32_bf16 v[72:75], v[172:175], v[220:223], v[72:75]
	v_mfma_f32_16x16x32_bf16 v[72:75], v[176:179], v[224:227], v[72:75]
	v_mfma_f32_16x16x32_bf16 v[88:91], v[176:179], v[216:219], v[88:91]
	v_mfma_f32_16x16x32_bf16 v[88:91], v[172:175], v[212:215], v[88:91]
	v_mfma_f32_16x16x32_bf16 v[104:107], v[172:175], v[204:207], v[104:107]
	v_mfma_f32_16x16x32_bf16 v[104:107], v[176:179], v[208:211], v[104:107]
	v_mfma_f32_16x16x32_bf16 v[120:123], v[176:179], v[200:203], v[120:123]
	v_mfma_f32_16x16x32_bf16 v[120:123], v[172:175], v[196:199], v[120:123]
	v_mfma_f32_16x16x32_bf16 v[116:119], v[180:183], v[196:199], v[116:119]
	v_mfma_f32_16x16x32_bf16 v[116:119], v[184:187], v[200:203], v[116:119]
	v_mfma_f32_16x16x32_bf16 v[100:103], v[184:187], v[208:211], v[100:103]
	v_mfma_f32_16x16x32_bf16 v[100:103], v[180:183], v[204:207], v[100:103]
	v_mfma_f32_16x16x32_bf16 v[84:87], v[180:183], v[212:215], v[84:87]
	v_mfma_f32_16x16x32_bf16 v[84:87], v[184:187], v[216:219], v[84:87]
	v_mfma_f32_16x16x32_bf16 v[68:71], v[184:187], v[224:227], v[68:71]
	v_mfma_f32_16x16x32_bf16 v[68:71], v[180:183], v[220:223], v[68:71]
	v_mfma_f32_16x16x32_bf16 v[64:67], v[188:191], v[220:223], v[64:67]
	v_mfma_f32_16x16x32_bf16 v[64:67], v[192:195], v[224:227], v[64:67]
	v_mfma_f32_16x16x32_bf16 v[80:83], v[192:195], v[216:219], v[80:83]
	v_mfma_f32_16x16x32_bf16 v[80:83], v[188:191], v[212:215], v[80:83]
	v_mfma_f32_16x16x32_bf16 v[96:99], v[188:191], v[204:207], v[96:99]
	v_mfma_f32_16x16x32_bf16 v[96:99], v[192:195], v[208:211], v[96:99]
	v_mfma_f32_16x16x32_bf16 v[112:115], v[192:195], v[200:203], v[112:115]
	v_mfma_f32_16x16x32_bf16 v[112:115], v[188:191], v[196:199], v[112:115]
	s_barrier
	s_add_i32 s20, s55, s30
	v_lshl_add_u64 v[160:161], v[160:161], 0, s[8:9]
	s_mov_b32 m0, s20
	s_nop 0
	global_load_lds_dwordx4 v[160:161], off
	s_add_i32 m0, s20, 0x2000
	s_add_u32 s20, s24, 0x100800
	v_lshl_add_u64 v[160:161], v[164:165], 0, s[8:9]
	s_addc_u32 s21, s25, 0
	s_add_i32 s24, s56, s30
	global_load_lds_dwordx4 v[160:161], off
	v_lshl_add_u64 v[160:161], s[20:21], 0, v[134:135]
	s_mov_b32 m0, s24
	s_nop 0
	global_load_lds_dwordx4 v[160:161], off
	v_lshl_add_u64 v[160:161], s[20:21], 0, v[138:139]
	s_add_i32 m0, s24, 0x2000
	s_nop 0
	global_load_lds_dwordx4 v[160:161], off
	v_lshl_add_u64 v[160:161], v[228:229], 0, s[8:9]
	s_mov_b32 m0, s41
	s_nop 0
	global_load_lds_dwordx4 v[160:161], off
	v_lshl_add_u64 v[160:161], v[230:231], 0, s[8:9]
	s_mov_b32 m0, s42
	s_nop 0
	global_load_lds_dwordx4 v[160:161], off
	ds_read_b128 v[196:199], v169 offset:49152
	ds_read_b128 v[200:203], v169 offset:50176
	ds_read_b128 v[204:207], v169 offset:51200
	ds_read_b128 v[208:211], v169 offset:52224
	ds_read_b128 v[212:215], v169 offset:53248
	ds_read_b128 v[216:219], v169 offset:54272
	ds_read_b128 v[220:223], v169 offset:55296
	ds_read_b128 v[224:227], v169 offset:56320
	s_waitcnt vmcnt(8)
	s_waitcnt lgkmcnt(0)
	s_barrier
	s_waitcnt lgkmcnt(0)
	v_mfma_f32_16x16x32_bf16 v[60:63], v[128:131], v[196:199], v[60:63]
	v_mfma_f32_16x16x32_bf16 v[60:63], v[154:157], v[200:203], v[60:63]
	v_mfma_f32_16x16x32_bf16 v[44:47], v[154:157], v[208:211], v[44:47]
	v_mfma_f32_16x16x32_bf16 v[44:47], v[128:131], v[204:207], v[44:47]
	v_mfma_f32_16x16x32_bf16 v[28:31], v[128:131], v[212:215], v[28:31]
	v_mfma_f32_16x16x32_bf16 v[28:31], v[154:157], v[216:219], v[28:31]
	v_mfma_f32_16x16x32_bf16 v[12:15], v[154:157], v[224:227], v[12:15]
	v_mfma_f32_16x16x32_bf16 v[12:15], v[128:131], v[220:223], v[12:15]
	v_mfma_f32_16x16x32_bf16 v[8:11], v[172:175], v[220:223], v[8:11]
	v_mfma_f32_16x16x32_bf16 v[8:11], v[176:179], v[224:227], v[8:11]
	v_mfma_f32_16x16x32_bf16 v[24:27], v[176:179], v[216:219], v[24:27]
	v_mfma_f32_16x16x32_bf16 v[24:27], v[172:175], v[212:215], v[24:27]
	v_mfma_f32_16x16x32_bf16 v[40:43], v[172:175], v[204:207], v[40:43]
	v_mfma_f32_16x16x32_bf16 v[40:43], v[176:179], v[208:211], v[40:43]
	v_mfma_f32_16x16x32_bf16 v[56:59], v[176:179], v[200:203], v[56:59]
	v_mfma_f32_16x16x32_bf16 v[56:59], v[172:175], v[196:199], v[56:59]
	v_mfma_f32_16x16x32_bf16 v[52:55], v[180:183], v[196:199], v[52:55]
	v_mfma_f32_16x16x32_bf16 v[52:55], v[184:187], v[200:203], v[52:55]
	v_mfma_f32_16x16x32_bf16 v[36:39], v[184:187], v[208:211], v[36:39]
	v_mfma_f32_16x16x32_bf16 v[36:39], v[180:183], v[204:207], v[36:39]
	v_mfma_f32_16x16x32_bf16 v[20:23], v[180:183], v[212:215], v[20:23]
	v_mfma_f32_16x16x32_bf16 v[20:23], v[184:187], v[216:219], v[20:23]
	v_mfma_f32_16x16x32_bf16 v[4:7], v[184:187], v[224:227], v[4:7]
	v_mfma_f32_16x16x32_bf16 v[4:7], v[180:183], v[220:223], v[4:7]
	v_mfma_f32_16x16x32_bf16 v[0:3], v[188:191], v[220:223], v[0:3]
	v_mfma_f32_16x16x32_bf16 v[0:3], v[192:195], v[224:227], v[0:3]
	v_mfma_f32_16x16x32_bf16 v[16:19], v[192:195], v[216:219], v[16:19]
	v_mfma_f32_16x16x32_bf16 v[16:19], v[188:191], v[212:215], v[16:19]
	v_mfma_f32_16x16x32_bf16 v[32:35], v[188:191], v[204:207], v[32:35]
	v_mfma_f32_16x16x32_bf16 v[32:35], v[192:195], v[208:211], v[32:35]
	v_mfma_f32_16x16x32_bf16 v[48:51], v[192:195], v[200:203], v[48:51]
	v_mfma_f32_16x16x32_bf16 v[48:51], v[188:191], v[196:199], v[48:51]
	s_barrier
	s_add_i32 s54, s54, 2
	s_add_u32 s52, s52, 0x1000
	s_addc_u32 s53, s53, 0
	s_cmp_gt_u32 s54, 61
	s_mov_b64 s[20:21], s[22:23]
	s_cbranch_scc0 .LBB0_1543
	s_and_b64 vcc, exec, s[4:5]
	s_cbranch_vccz .LBB0_1546
	s_barrier

.LBB0_1625:
	ds_read_b128 v[128:131], v177
	ds_read_b128 v[132:135], v177 offset:1024
	ds_read_b128 v[136:139], v177 offset:2048
	ds_read_b128 v[140:143], v177 offset:3072
	ds_read_b128 v[144:147], v178
	ds_read_b128 v[148:151], v178 offset:1024
	ds_read_b128 v[170:173], v178 offset:2048
	ds_read_b128 v[182:185], v178 offset:3072
	s_add_u32 s24, s22, 0xffc00800
	s_addc_u32 s25, s23, -1
	s_cmpk_eq_i32 s57, 0xfc
	s_cselect_b32 s27, s29, s25
	s_cselect_b32 s26, s53, s24
	s_cselect_b32 s25, s17, s56
	s_cselect_b32 s24, s54, s55
	v_lshl_add_u64 v[186:187], s[22:23], 0, v[162:163]
	s_add_i32 m0, s38, 0xc000
	s_nop 0
	global_load_lds_dwordx4 v[186:187], off
	v_lshl_add_u64 v[186:187], s[22:23], 0, v[164:165]
	s_add_i32 m0, s38, 0xe000
	s_nop 0
	global_load_lds_dwordx4 v[186:187], off
	ds_read_b128 v[186:189], v179
	ds_read_b128 v[190:193], v179 offset:1024
	ds_read_b128 v[194:197], v179 offset:2048
	ds_read_b128 v[198:201], v179 offset:3072
	ds_read_b128 v[202:205], v179 offset:4096
	ds_read_b128 v[206:209], v179 offset:5120
	ds_read_b128 v[210:213], v179 offset:6144
	ds_read_b128 v[214:217], v179 offset:7168
	s_waitcnt vmcnt(8)
	s_waitcnt lgkmcnt(0)
	s_barrier
	s_waitcnt lgkmcnt(0)
	v_mfma_f32_16x16x32_bf16 v[124:127], v[128:131], v[186:189], v[124:127]
	v_mfma_f32_16x16x32_bf16 v[124:127], v[132:135], v[190:193], v[124:127]
	v_mfma_f32_16x16x32_bf16 v[108:111], v[132:135], v[198:201], v[108:111]
	v_mfma_f32_16x16x32_bf16 v[108:111], v[128:131], v[194:197], v[108:111]
	v_mfma_f32_16x16x32_bf16 v[92:95], v[128:131], v[202:205], v[92:95]
	v_mfma_f32_16x16x32_bf16 v[92:95], v[132:135], v[206:209], v[92:95]
	v_mfma_f32_16x16x32_bf16 v[76:79], v[132:135], v[214:217], v[76:79]
	v_mfma_f32_16x16x32_bf16 v[76:79], v[128:131], v[210:213], v[76:79]
	v_mfma_f32_16x16x32_bf16 v[72:75], v[136:139], v[210:213], v[72:75]
	v_mfma_f32_16x16x32_bf16 v[72:75], v[140:143], v[214:217], v[72:75]
	v_mfma_f32_16x16x32_bf16 v[88:91], v[140:143], v[206:209], v[88:91]
	v_mfma_f32_16x16x32_bf16 v[88:91], v[136:139], v[202:205], v[88:91]
	v_mfma_f32_16x16x32_bf16 v[104:107], v[136:139], v[194:197], v[104:107]
	v_mfma_f32_16x16x32_bf16 v[104:107], v[140:143], v[198:201], v[104:107]
	v_mfma_f32_16x16x32_bf16 v[120:123], v[140:143], v[190:193], v[120:123]
	v_mfma_f32_16x16x32_bf16 v[120:123], v[136:139], v[186:189], v[120:123]
	v_mfma_f32_16x16x32_bf16 v[116:119], v[144:147], v[186:189], v[116:119]
	v_mfma_f32_16x16x32_bf16 v[116:119], v[148:151], v[190:193], v[116:119]
	v_mfma_f32_16x16x32_bf16 v[100:103], v[148:151], v[198:201], v[100:103]
	v_mfma_f32_16x16x32_bf16 v[100:103], v[144:147], v[194:197], v[100:103]
	v_mfma_f32_16x16x32_bf16 v[84:87], v[144:147], v[202:205], v[84:87]
	v_mfma_f32_16x16x32_bf16 v[84:87], v[148:151], v[206:209], v[84:87]
	v_mfma_f32_16x16x32_bf16 v[68:71], v[148:151], v[214:217], v[68:71]
	v_mfma_f32_16x16x32_bf16 v[68:71], v[144:147], v[210:213], v[68:71]
	v_mfma_f32_16x16x32_bf16 v[64:67], v[170:173], v[210:213], v[64:67]
	v_mfma_f32_16x16x32_bf16 v[64:67], v[182:185], v[214:217], v[64:67]
	v_mfma_f32_16x16x32_bf16 v[80:83], v[182:185], v[206:209], v[80:83]
	v_mfma_f32_16x16x32_bf16 v[80:83], v[170:173], v[202:205], v[80:83]
	v_mfma_f32_16x16x32_bf16 v[96:99], v[170:173], v[194:197], v[96:99]
	v_mfma_f32_16x16x32_bf16 v[96:99], v[182:185], v[198:201], v[96:99]
	v_mfma_f32_16x16x32_bf16 v[112:115], v[182:185], v[190:193], v[112:115]
	v_mfma_f32_16x16x32_bf16 v[112:115], v[170:173], v[186:189], v[112:115]
	s_barrier
	s_add_i32 s58, s48, s37
	v_lshl_add_u64 v[218:219], s[24:25], 0, v[154:155]
	s_mov_b32 m0, s58
	v_lshl_add_u64 v[220:221], s[24:25], 0, v[158:159]
	global_load_lds_dwordx4 v[218:219], off
	s_add_i32 m0, s58, 0x2000
	s_add_u32 s58, s24, 0x400000
	s_addc_u32 s59, s25, 0
	s_add_i32 s60, s49, s37
	global_load_lds_dwordx4 v[220:221], off
	v_lshl_add_u64 v[186:187], s[58:59], 0, v[154:155]
	s_mov_b32 m0, s60
	v_lshl_add_u64 v[222:223], s[26:27], 0, v[152:153]
	global_load_lds_dwordx4 v[186:187], off
	v_lshl_add_u64 v[186:187], s[58:59], 0, v[158:159]
	s_add_i32 m0, s60, 0x2000
	v_lshl_add_u64 v[224:225], s[26:27], 0, v[156:157]
	global_load_lds_dwordx4 v[186:187], off
	s_mov_b32 m0, s38
	s_nop 0
	global_load_lds_dwordx4 v[222:223], off
	s_mov_b32 m0, s39
	s_nop 0
	global_load_lds_dwordx4 v[224:225], off
	ds_read_b128 v[186:189], v179 offset:16384
	ds_read_b128 v[190:193], v179 offset:17408
	ds_read_b128 v[194:197], v179 offset:18432
	ds_read_b128 v[198:201], v179 offset:19456
	ds_read_b128 v[202:205], v179 offset:20480
	ds_read_b128 v[206:209], v179 offset:21504
	ds_read_b128 v[210:213], v179 offset:22528
	ds_read_b128 v[214:217], v179 offset:23552
	s_waitcnt vmcnt(8)
	s_waitcnt lgkmcnt(0)
	s_barrier
	s_waitcnt lgkmcnt(0)
	v_mfma_f32_16x16x32_bf16 v[60:63], v[128:131], v[186:189], v[60:63]
	v_mfma_f32_16x16x32_bf16 v[60:63], v[132:135], v[190:193], v[60:63]
	v_mfma_f32_16x16x32_bf16 v[44:47], v[132:135], v[198:201], v[44:47]
	v_mfma_f32_16x16x32_bf16 v[44:47], v[128:131], v[194:197], v[44:47]
	v_mfma_f32_16x16x32_bf16 v[28:31], v[128:131], v[202:205], v[28:31]
	v_mfma_f32_16x16x32_bf16 v[28:31], v[132:135], v[206:209], v[28:31]
	v_mfma_f32_16x16x32_bf16 v[12:15], v[132:135], v[214:217], v[12:15]
	v_mfma_f32_16x16x32_bf16 v[12:15], v[128:131], v[210:213], v[12:15]
	v_mfma_f32_16x16x32_bf16 v[8:11], v[136:139], v[210:213], v[8:11]
	v_mfma_f32_16x16x32_bf16 v[8:11], v[140:143], v[214:217], v[8:11]
	v_mfma_f32_16x16x32_bf16 v[24:27], v[140:143], v[206:209], v[24:27]
	v_mfma_f32_16x16x32_bf16 v[24:27], v[136:139], v[202:205], v[24:27]
	v_mfma_f32_16x16x32_bf16 v[40:43], v[136:139], v[194:197], v[40:43]
	v_mfma_f32_16x16x32_bf16 v[40:43], v[140:143], v[198:201], v[40:43]
	v_mfma_f32_16x16x32_bf16 v[56:59], v[140:143], v[190:193], v[56:59]
	v_mfma_f32_16x16x32_bf16 v[56:59], v[136:139], v[186:189], v[56:59]
	v_mfma_f32_16x16x32_bf16 v[52:55], v[144:147], v[186:189], v[52:55]
	v_mfma_f32_16x16x32_bf16 v[52:55], v[148:151], v[190:193], v[52:55]
	v_mfma_f32_16x16x32_bf16 v[36:39], v[148:151], v[198:201], v[36:39]
	v_mfma_f32_16x16x32_bf16 v[36:39], v[144:147], v[194:197], v[36:39]
	v_mfma_f32_16x16x32_bf16 v[20:23], v[144:147], v[202:205], v[20:23]
	v_mfma_f32_16x16x32_bf16 v[20:23], v[148:151], v[206:209], v[20:23]
	v_mfma_f32_16x16x32_bf16 v[4:7], v[148:151], v[214:217], v[4:7]
	v_mfma_f32_16x16x32_bf16 v[4:7], v[144:147], v[210:213], v[4:7]
	v_mfma_f32_16x16x32_bf16 v[0:3], v[170:173], v[210:213], v[0:3]
	v_mfma_f32_16x16x32_bf16 v[0:3], v[182:185], v[214:217], v[0:3]
	v_mfma_f32_16x16x32_bf16 v[16:19], v[182:185], v[206:209], v[16:19]
	v_mfma_f32_16x16x32_bf16 v[16:19], v[170:173], v[202:205], v[16:19]
	v_mfma_f32_16x16x32_bf16 v[32:35], v[170:173], v[194:197], v[32:35]
	v_mfma_f32_16x16x32_bf16 v[32:35], v[182:185], v[198:201], v[32:35]
	v_mfma_f32_16x16x32_bf16 v[48:51], v[182:185], v[190:193], v[48:51]
	v_mfma_f32_16x16x32_bf16 v[48:51], v[170:173], v[186:189], v[48:51]
	s_barrier
	s_add_i32 s58, 0, 0x18000
	s_add_i32 s59, 0, 0x1c000
	v_add_u32_e32 v140, s58, v174
	v_add_u32_e32 v181, s59, v174
	ds_read_b128 v[128:131], v140
	ds_read_b128 v[132:135], v140 offset:1024
	ds_read_b128 v[136:139], v140 offset:2048
	ds_read_b128 v[140:143], v140 offset:3072
	ds_read_b128 v[144:147], v181
	ds_read_b128 v[148:151], v181 offset:1024
	ds_read_b128 v[170:173], v181 offset:2048
	ds_read_b128 v[182:185], v181 offset:3072
	s_add_u32 s26, s26, 0x400000
	s_addc_u32 s27, s27, 0
	s_mov_b32 m0, s40
	v_lshl_add_u64 v[186:187], s[26:27], 0, v[152:153]
	global_load_lds_dwordx4 v[186:187], off
	v_lshl_add_u64 v[186:187], s[26:27], 0, v[156:157]
	s_mov_b32 m0, s41
	s_nop 0
	global_load_lds_dwordx4 v[186:187], off
	ds_read_b128 v[186:189], v179 offset:32768
	ds_read_b128 v[190:193], v179 offset:33792
	ds_read_b128 v[194:197], v179 offset:34816
	ds_read_b128 v[198:201], v179 offset:35840
	ds_read_b128 v[202:205], v179 offset:36864
	ds_read_b128 v[206:209], v179 offset:37888
	ds_read_b128 v[210:213], v179 offset:38912
	ds_read_b128 v[214:217], v179 offset:39936
	s_waitcnt vmcnt(8)
	s_waitcnt lgkmcnt(0)
	s_barrier
	s_waitcnt lgkmcnt(0)
	v_mfma_f32_16x16x32_bf16 v[124:127], v[128:131], v[186:189], v[124:127]
	v_mfma_f32_16x16x32_bf16 v[124:127], v[132:135], v[190:193], v[124:127]
	v_mfma_f32_16x16x32_bf16 v[108:111], v[132:135], v[198:201], v[108:111]
	v_mfma_f32_16x16x32_bf16 v[108:111], v[128:131], v[194:197], v[108:111]
	v_mfma_f32_16x16x32_bf16 v[92:95], v[128:131], v[202:205], v[92:95]
	v_mfma_f32_16x16x32_bf16 v[92:95], v[132:135], v[206:209], v[92:95]
	v_mfma_f32_16x16x32_bf16 v[76:79], v[132:135], v[214:217], v[76:79]
	v_mfma_f32_16x16x32_bf16 v[76:79], v[128:131], v[210:213], v[76:79]
	v_mfma_f32_16x16x32_bf16 v[72:75], v[136:139], v[210:213], v[72:75]
	v_mfma_f32_16x16x32_bf16 v[72:75], v[140:143], v[214:217], v[72:75]
	v_mfma_f32_16x16x32_bf16 v[88:91], v[140:143], v[206:209], v[88:91]
	v_mfma_f32_16x16x32_bf16 v[88:91], v[136:139], v[202:205], v[88:91]
	v_mfma_f32_16x16x32_bf16 v[104:107], v[136:139], v[194:197], v[104:107]
	v_mfma_f32_16x16x32_bf16 v[104:107], v[140:143], v[198:201], v[104:107]
	v_mfma_f32_16x16x32_bf16 v[120:123], v[140:143], v[190:193], v[120:123]
	v_mfma_f32_16x16x32_bf16 v[120:123], v[136:139], v[186:189], v[120:123]
	v_mfma_f32_16x16x32_bf16 v[116:119], v[144:147], v[186:189], v[116:119]
	v_mfma_f32_16x16x32_bf16 v[116:119], v[148:151], v[190:193], v[116:119]
	v_mfma_f32_16x16x32_bf16 v[100:103], v[148:151], v[198:201], v[100:103]
	v_mfma_f32_16x16x32_bf16 v[100:103], v[144:147], v[194:197], v[100:103]
	v_mfma_f32_16x16x32_bf16 v[84:87], v[144:147], v[202:205], v[84:87]
	v_mfma_f32_16x16x32_bf16 v[84:87], v[148:151], v[206:209], v[84:87]
	v_mfma_f32_16x16x32_bf16 v[68:71], v[148:151], v[214:217], v[68:71]
	v_mfma_f32_16x16x32_bf16 v[68:71], v[144:147], v[210:213], v[68:71]
	v_mfma_f32_16x16x32_bf16 v[64:67], v[170:173], v[210:213], v[64:67]
	v_mfma_f32_16x16x32_bf16 v[64:67], v[182:185], v[214:217], v[64:67]
	v_mfma_f32_16x16x32_bf16 v[80:83], v[182:185], v[206:209], v[80:83]
	v_mfma_f32_16x16x32_bf16 v[80:83], v[170:173], v[202:205], v[80:83]
	v_mfma_f32_16x16x32_bf16 v[96:99], v[170:173], v[194:197], v[96:99]
	v_mfma_f32_16x16x32_bf16 v[96:99], v[182:185], v[198:201], v[96:99]
	v_mfma_f32_16x16x32_bf16 v[112:115], v[182:185], v[190:193], v[112:115]
	v_mfma_f32_16x16x32_bf16 v[112:115], v[170:173], v[186:189], v[112:115]
	s_barrier
	s_add_i32 s26, s58, s37
	v_lshl_add_u64 v[186:187], v[218:219], 0, s[14:15]
	s_mov_b32 m0, s26
	s_nop 0
	global_load_lds_dwordx4 v[186:187], off
	s_add_i32 m0, s26, 0x2000
	s_add_u32 s24, s24, 0x400800
	v_lshl_add_u64 v[186:187], v[220:221], 0, s[14:15]
	s_addc_u32 s25, s25, 0
	s_add_i32 s26, s59, s37
	global_load_lds_dwordx4 v[186:187], off
	v_lshl_add_u64 v[186:187], s[24:25], 0, v[154:155]
	s_mov_b32 m0, s26
	s_nop 0
	global_load_lds_dwordx4 v[186:187], off
	v_lshl_add_u64 v[186:187], s[24:25], 0, v[158:159]
	s_add_i32 m0, s26, 0x2000
	s_nop 0
	global_load_lds_dwordx4 v[186:187], off
	v_lshl_add_u64 v[186:187], v[222:223], 0, s[14:15]
	s_mov_b32 m0, s43
	s_nop 0
	global_load_lds_dwordx4 v[186:187], off
	v_lshl_add_u64 v[186:187], v[224:225], 0, s[14:15]
	s_mov_b32 m0, s44
	s_nop 0
	global_load_lds_dwordx4 v[186:187], off
	ds_read_b128 v[186:189], v179 offset:49152
	ds_read_b128 v[190:193], v179 offset:50176
	ds_read_b128 v[194:197], v179 offset:51200
	ds_read_b128 v[198:201], v179 offset:52224
	ds_read_b128 v[202:205], v179 offset:53248
	ds_read_b128 v[206:209], v179 offset:54272
	ds_read_b128 v[210:213], v179 offset:55296
	ds_read_b128 v[214:217], v179 offset:56320
	s_waitcnt vmcnt(8)
	s_waitcnt lgkmcnt(0)
	s_barrier
	s_waitcnt lgkmcnt(0)
	v_mfma_f32_16x16x32_bf16 v[60:63], v[128:131], v[186:189], v[60:63]
	v_mfma_f32_16x16x32_bf16 v[60:63], v[132:135], v[190:193], v[60:63]
	v_mfma_f32_16x16x32_bf16 v[44:47], v[132:135], v[198:201], v[44:47]
	v_mfma_f32_16x16x32_bf16 v[44:47], v[128:131], v[194:197], v[44:47]
	v_mfma_f32_16x16x32_bf16 v[28:31], v[128:131], v[202:205], v[28:31]
	v_mfma_f32_16x16x32_bf16 v[28:31], v[132:135], v[206:209], v[28:31]
	v_mfma_f32_16x16x32_bf16 v[12:15], v[132:135], v[214:217], v[12:15]
	v_mfma_f32_16x16x32_bf16 v[12:15], v[128:131], v[210:213], v[12:15]
	v_mfma_f32_16x16x32_bf16 v[8:11], v[136:139], v[210:213], v[8:11]
	v_mfma_f32_16x16x32_bf16 v[8:11], v[140:143], v[214:217], v[8:11]
	v_mfma_f32_16x16x32_bf16 v[24:27], v[140:143], v[206:209], v[24:27]
	v_mfma_f32_16x16x32_bf16 v[24:27], v[136:139], v[202:205], v[24:27]
	v_mfma_f32_16x16x32_bf16 v[40:43], v[136:139], v[194:197], v[40:43]
	v_mfma_f32_16x16x32_bf16 v[40:43], v[140:143], v[198:201], v[40:43]
	v_mfma_f32_16x16x32_bf16 v[56:59], v[140:143], v[190:193], v[56:59]
	v_mfma_f32_16x16x32_bf16 v[56:59], v[136:139], v[186:189], v[56:59]
	v_mfma_f32_16x16x32_bf16 v[52:55], v[144:147], v[186:189], v[52:55]
	v_mfma_f32_16x16x32_bf16 v[52:55], v[148:151], v[190:193], v[52:55]
	v_mfma_f32_16x16x32_bf16 v[36:39], v[148:151], v[198:201], v[36:39]
	v_mfma_f32_16x16x32_bf16 v[36:39], v[144:147], v[194:197], v[36:39]
	v_mfma_f32_16x16x32_bf16 v[20:23], v[144:147], v[202:205], v[20:23]
	v_mfma_f32_16x16x32_bf16 v[20:23], v[148:151], v[206:209], v[20:23]
	v_mfma_f32_16x16x32_bf16 v[4:7], v[148:151], v[214:217], v[4:7]
	v_mfma_f32_16x16x32_bf16 v[4:7], v[144:147], v[210:213], v[4:7]
	v_mfma_f32_16x16x32_bf16 v[0:3], v[170:173], v[210:213], v[0:3]
	v_mfma_f32_16x16x32_bf16 v[0:3], v[182:185], v[214:217], v[0:3]
	v_mfma_f32_16x16x32_bf16 v[16:19], v[182:185], v[206:209], v[16:19]
	v_mfma_f32_16x16x32_bf16 v[16:19], v[170:173], v[202:205], v[16:19]
	v_mfma_f32_16x16x32_bf16 v[32:35], v[170:173], v[194:197], v[32:35]
	v_mfma_f32_16x16x32_bf16 v[32:35], v[182:185], v[198:201], v[32:35]
	v_mfma_f32_16x16x32_bf16 v[48:51], v[182:185], v[190:193], v[48:51]
	v_mfma_f32_16x16x32_bf16 v[48:51], v[170:173], v[186:189], v[48:51]
	s_barrier
	s_add_i32 s57, s57, 2
	s_add_u32 s22, s22, 0x1000
	s_addc_u32 s23, s23, 0
	s_add_u32 s55, s55, 0x1000
	s_addc_u32 s56, s56, 0
	s_cmpk_gt_u32 s57, 0xfd
	s_cbranch_scc0 .LBB0_1625
	s_and_b64 vcc, exec, s[6:7]
	s_cbranch_vccz .LBB0_1628
	s_barrier
